# P3 scan: per-token y select folded into the last DPP step (bank_mask write into 4 accumulators, 3 selects per 16 tokens instead of 16)
# baseline (speedup 1.0000x reference)
; __device__ __forceinline__ float row_sum16(float x) { x = dpp_add<0xB1>(x); x = dpp_add<0x4E>(x); x = dpp_add<0x124>(x); x = dpp_add<0x128>(x); return x; }
; __device__ __forceinline__ void rwkv_scan_prompt(const Params& p, LAS unsigned char* lds, int bh, int rq) {
;     ...
;                 if (tk > 0) yk[(tk - 1) >> 4] = (cg_ == ((tk - 1) & 15)) ? yp : yk[(tk - 1) >> 4];
;                 S = sa * b4 + T;
;                 rp = r4;
;                 r4 = nr4; d4 = nd4; k4 = nk4; a4 = na4; b4 = nb4; vv = nvv;
;             }
;             {
;                 float yp = S[0] * rp[0] + S[1] * rp[1] + S[2] * rp[2] + S[3] * rp[3];
;                 yp = row_sum16(yp);
;                 yk[(TC - 1) >> 4] = (cg_ == ((TC - 1) & 15)) ? yp : yk[(TC - 1) >> 4];
.LBB0_308:
	s_or_b64 exec, exec, s[0:1]
	s_cmpk_lt_i32 s2, 0x100
	s_movk_i32 s0, 0x100
	s_cselect_b64 s[76:77], -1, 0
	s_cmpk_gt_i32 s2, 0xff
	v_lshlrev_b32_e32 v36, 2, v131
	v_cmp_eq_u32_e64 s[4:5], 15, v131
	v_cmp_eq_u32_e64 s[6:7], 0, v131
	v_cmp_eq_u32_e64 s[8:9], 1, v131
	v_cmp_eq_u32_e64 s[10:11], 2, v131
	v_cmp_eq_u32_e64 s[12:13], 3, v131
	v_cmp_eq_u32_e64 s[14:15], 4, v131
	v_cmp_eq_u32_e64 s[16:17], 5, v131
	v_cmp_eq_u32_e64 s[18:19], 6, v131
	v_cmp_eq_u32_e64 s[20:21], 7, v131
	v_cmp_eq_u32_e64 s[22:23], 8, v131
	v_cmp_eq_u32_e64 s[24:25], 9, v131
	v_cmp_eq_u32_e64 s[26:27], 10, v131
	v_cmp_eq_u32_e64 s[28:29], 11, v131
	v_cmp_eq_u32_e64 s[30:31], 12, v131
	v_cmp_eq_u32_e64 s[34:35], 13, v131
	v_cmp_eq_u32_e64 s[36:37], 14, v131
	v_and_b32_e32 v211, 3, v131
	v_cmp_eq_u32_e64 s[96:97], 1, v211
	v_cmp_eq_u32_e64 s[98:99], 2, v211
	v_cmp_eq_u32_e64 s[100:101], 3, v211
	v_lshlrev_b32_e32 v52, 4, v131
	s_barrier
	s_cbranch_scc1 .LBB0_360
; #define LAS __attribute__((address_space(3)))
; __device__ __forceinline__ void rwkv_scan_prompt(const Params& p, LAS unsigned char* lds, int bh, int rq) {
;     ...
;     const int rr = lane >> 4, cg_ = lane & 15, rloc = (wave & 3) * 4 + rr;
;     const int ltid = tid - 256;
;     f32x4 S = {0.f, 0.f, 0.f, 0.f};
;     h16x8 pre[NPIECE]; float prk = 0.f;
;     auto issue_chunk = [&](int c) {
; #pragma unroll
;         for (int i = 0; i < NPIECE; ++i) {
;             const int piece = ltid + 256 * i, tk = piece / 48, q = piece % 48, vec = q >> 3, c8 = q & 7;
;             pre[i] = *(const h16x8*)(OPSG + (((size_t)(rowbase + c * TC + tk) * 8 + h) * 6 + vec) * 64 + c8 * 8);
;         }
;         if (ltid < TC) prk = RKS[(size_t)(rowbase + c * TC + ltid) * 8 + h];
;     };
;     auto store_chunk = [&](int buf) {
; #pragma unroll
;         for (int i = 0; i < NPIECE; ++i) {
;             const int piece = ltid + 256 * i, tk = piece / 48, q = piece % 48, vec = q >> 3, c8 = q & 7;
;             const h16x8 v = pre[i];
;             f32x4 a, bb;
; #pragma unroll
;             for (int j = 0; j < 4; ++j) { a[j] = (float)v[j]; bb[j] = (float)v[4 + j]; }
;             if (vec == 1) {
; #pragma unroll
;                 for (int j = 0; j < 4; ++j) { a[j] = __expf(a[j]); bb[j] = __expf(bb[j]); }
;             }
;             LAS float* d = OPS + ((buf * TC + tk) * 6 + vec) * 64 + c8 * 8;
;             *(LAS f32x4*)d = a; *(LAS f32x4*)(d + 4) = bb;
;         }
;         if (ltid < TC) RKB[buf * TC + ltid] = prk;
;     };
	v_add_u16_e32 v3, 0x100, v132
	v_mul_u32_u24_e32 v4, 0x556, v3
	v_lshrrev_b32_e32 v57, 16, v4
	v_mul_lo_u16_e32 v4, 48, v57
	v_sub_u16_e32 v63, v3, v4
	v_lshlrev_b32_e32 v3, 3, v63
	v_and_b32_e32 v46, 56, v3
	v_add_u16_e32 v3, 0x200, v132
	v_mul_u32_u24_e32 v4, 0x556, v3
	v_lshrrev_b32_e32 v65, 16, v4
	v_subrev_co_u32_e32 v37, vcc, 0x100, v132
	v_cmp_gt_u32_e64 s[38:39], s0, v132
	s_mov_b32 s0, 0xaaab
	v_mul_lo_u16_e32 v4, 48, v65
	v_mul_u32_u24_sdwa v1, v37, s0 dst_sel:DWORD dst_unused:UNUSED_PAD src0_sel:WORD_0 src1_sel:DWORD
	v_sub_u16_e32 v67, v3, v4
	v_lshrrev_b32_e32 v47, 21, v1
	v_mul_u32_u24_e32 v2, 0x556, v132
	v_lshlrev_b32_e32 v3, 3, v67
	v_mul_lo_u16_e32 v1, 48, v47
	v_lshrrev_b32_e32 v51, 16, v2
	v_and_b32_e32 v50, 56, v3
	v_add_u16_e32 v3, 0x300, v132
	v_sub_u16_e32 v1, v37, v1
	v_mul_lo_u16_e32 v2, 48, v51
	v_mul_u32_u24_e32 v4, 0x556, v3
	v_lshrrev_b32_e32 v38, 3, v1
	v_lshlrev_b32_e32 v1, 3, v1
	v_sub_u16_e32 v2, v132, v2
	v_lshrrev_b32_e32 v108, 16, v4
	v_and_b32_e32 v1, 56, v1
	v_lshrrev_b32_e32 v42, 3, v2
	v_lshlrev_b32_e32 v2, 3, v2
	v_mul_lo_u16_e32 v4, 48, v108
	v_mul_u32_u24_e32 v5, 6, v47
	v_and_b32_e32 v2, 56, v2
	v_sub_u16_e32 v109, v3, v4
	v_add_lshl_u32 v5, v5, v38, 8
	v_lshlrev_b32_e32 v6, 2, v1
	s_movk_i32 s0, 0x556
	v_lshlrev_b32_e32 v3, 3, v109
	v_or_b32_e32 v4, 0x400, v132
	v_add3_u32 v111, 0, v5, v6
	v_mad_u32_u24 v5, v51, 6, v42
	v_lshl_add_u32 v112, v2, 2, 0
	v_lshrrev_b32_e32 v44, 3, v63
	v_and_b32_e32 v56, 56, v3
	v_mul_u32_u24_sdwa v3, v4, s0 dst_sel:DWORD dst_unused:UNUSED_PAD src0_sel:WORD_0 src1_sel:DWORD
	v_lshl_add_u32 v113, v5, 8, v112
	v_mul_u32_u24_e32 v5, 6, v57
	v_lshrrev_b32_e32 v110, 16, v3
	v_add_lshl_u32 v5, v5, v44, 8
	v_lshlrev_b32_e32 v6, 2, v46
	v_lshrrev_b32_e32 v48, 3, v67
	v_mul_lo_u16_e32 v3, 48, v110
	v_add3_u32 v114, 0, v5, v6
	v_mul_u32_u24_e32 v5, 6, v65
	v_sub_u16_e32 v3, v4, v3
	v_add_lshl_u32 v5, v5, v48, 8
	v_lshlrev_b32_e32 v6, 2, v50
	v_lshrrev_b32_e32 v54, 3, v109
	v_lshrrev_b32_e32 v58, 3, v3
	v_lshlrev_b32_e32 v3, 3, v3
	v_add3_u32 v115, 0, v5, v6
	v_mul_u32_u24_e32 v5, 6, v108
	v_and_b32_e32 v3, 56, v3
	v_add_lshl_u32 v5, v5, v54, 8
	v_lshlrev_b32_e32 v6, 2, v56
	v_add3_u32 v116, 0, v5, v6
	v_mad_u32_u24 v5, v110, 6, v58
	v_lshl_add_u32 v117, v3, 2, 0
	v_lshl_add_u32 v118, v5, 8, v117
	v_mul_i32_i24_e32 v5, 0x2aab, v37
	v_mov_b32_e32 v6, 3
	v_ashrrev_i16_sdwa v7, v6, v5 dst_sel:DWORD dst_unused:UNUSED_PAD src0_sel:DWORD src1_sel:WORD_1
	v_lshrrev_b32_e32 v5, 31, v5
	v_add_u16_e32 v127, v7, v5
	v_mul_lo_u16_e32 v5, 48, v127
	v_sub_u16_e32 v5, v37, v5
	v_ashrrev_i32_sdwa v60, v6, sext(v5) dst_sel:DWORD dst_unused:UNUSED_PAD src0_sel:DWORD src1_sel:WORD_0
	v_lshlrev_b32_sdwa v5, v6, sext(v5) dst_sel:DWORD dst_unused:UNUSED_PAD src0_sel:DWORD src1_sel:WORD_0
	v_or_b32_e32 v6, 0x100, v132
	v_mul_u32_u24_sdwa v7, v6, s0 dst_sel:DWORD dst_unused:UNUSED_PAD src0_sel:WORD_0 src1_sel:DWORD
	v_lshrrev_b32_e32 v137, 16, v7
	v_mul_lo_u16_e32 v7, 48, v137
	v_sub_u16_e32 v139, v6, v7
	v_lshlrev_b32_e32 v6, 3, v139
	v_and_b32_e32 v62, 56, v6
	v_or_b32_e32 v6, 0x200, v132
	v_mul_u32_u24_sdwa v7, v6, s0 dst_sel:DWORD dst_unused:UNUSED_PAD src0_sel:WORD_0 src1_sel:DWORD
	v_lshrrev_b32_e32 v141, 16, v7
	v_mul_lo_u16_e32 v7, 48, v141
	v_sub_u16_e32 v143, v6, v7
	v_mov_b32_e32 v41, 0
	v_lshlrev_b32_e32 v6, 3, v143
	v_lshlrev_b32_e32 v40, 1, v1
	v_and_b32_e32 v64, 56, v6
	v_or_b32_e32 v6, 0x300, v132
	v_lshl_add_u64 v[68:69], s[86:87], 0, v[40:41]
	v_lshlrev_b32_e32 v40, 1, v2
	v_mul_u32_u24_sdwa v7, v6, s0 dst_sel:DWORD dst_unused:UNUSED_PAD src0_sel:WORD_0 src1_sel:DWORD
	v_lshl_add_u64 v[70:71], s[86:87], 0, v[40:41]
	v_lshlrev_b32_e32 v40, 1, v46
	v_lshrrev_b32_e32 v145, 16, v7
	v_lshl_add_u64 v[72:73], s[86:87], 0, v[40:41]
	v_lshlrev_b32_e32 v40, 1, v50
	v_mul_lo_u16_e32 v7, 48, v145
	v_lshl_add_u64 v[74:75], s[86:87], 0, v[40:41]
	v_lshlrev_b32_e32 v40, 1, v56
	v_readlane_b32 s60, v253, 20
	s_mov_b32 s0, 0x5555556
	s_add_i32 s3, 0, 0x18000
	v_and_b32_e32 v5, 56, v5
	v_sub_u16_e32 v147, v6, v7
	v_lshl_add_u64 v[76:77], s[86:87], 0, v[40:41]
	v_lshlrev_b32_e32 v40, 1, v3
	v_mov_b32_e32 v53, v41
	v_readlane_b32 s74, v253, 34
	v_readlane_b32 s75, v253, 35
	v_mul_hi_u32 v1, v4, s0
	v_bfe_u32 v0, v132, 4, 4
	v_lshl_add_u32 v119, v37, 2, s3
	v_add_u32_e32 v126, s3, v36
	s_movk_i32 s3, 0x120
	v_lshlrev_b32_e32 v6, 3, v147
	s_add_u32 s84, s82, 0x1aec800
	v_lshl_add_u64 v[78:79], s[86:87], 0, v[40:41]
	v_lshlrev_b32_e32 v40, 1, v5
	v_lshl_add_u64 v[2:3], s[74:75], 0, v[52:53]
	s_mov_b64 s[58:59], 0x419c100
	v_or_b32_e32 v148, 64, v1
	v_mov_b32_e32 v1, 64
	v_mov_b32_e32 v39, v41
	v_mov_b32_e32 v43, v41
	v_mov_b32_e32 v45, v41
	v_mov_b32_e32 v49, v41
	v_mov_b32_e32 v55, v41
	v_mov_b32_e32 v59, v41
	v_cmp_gt_u32_e64 s[40:41], 32, v37
	v_cmp_ne_u32_e64 s[42:43], 1, v38
	s_mov_b32 s1, 0
	v_cmp_ne_u32_e64 s[44:45], 1, v42
	v_cmp_ne_u32_e64 s[46:47], 1, v44
	v_cmp_ne_u32_e64 s[48:49], 1, v48
	v_cmp_ne_u32_e64 s[50:51], 1, v54
	v_cmp_ne_u32_e64 s[52:53], 1, v58
	v_add_u32_e32 v120, 32, v47
	v_add_u32_e32 v121, 32, v57
	v_add_u32_e32 v122, 32, v65
	v_add_u32_e32 v123, 32, v108
	v_add_u32_e32 v124, 32, v110
	v_add_u32_e32 v125, 0xffffff20, v132
	v_cmp_ne_u32_e64 s[54:55], 1, v60
	v_lshl_add_u32 v129, v5, 2, 0
	v_cmp_gt_u32_e64 s[56:57], s3, v132
	v_ashrrev_i32_e32 v61, 31, v60
	v_mul_u32_u24_e32 v135, 0x600, v131
	v_and_b32_e32 v66, 56, v6
	s_addc_u32 s85, s83, 0
	v_lshl_add_u64 v[80:81], s[86:87], 0, v[40:41]
	v_lshl_add_u64 v[82:83], v[2:3], 0, s[58:59]
	v_add_u32_e32 v53, 0xffffff40, v132
	v_or_b32_e32 v149, 64, v51
	v_add_u32_sdwa v150, sext(v127), v1 dst_sel:DWORD dst_unused:UNUSED_PAD src0_sel:WORD_0 src1_sel:DWORD
	v_lshlrev_b32_e32 v84, 2, v0
	s_mov_b32 s3, s2
	v_readlane_b32 s61, v253, 21
	v_readlane_b32 s62, v253, 22
	v_readlane_b32 s63, v253, 23
	v_readlane_b32 s64, v253, 24
	v_readlane_b32 s65, v253, 25
	v_readlane_b32 s66, v253, 26
	v_readlane_b32 s67, v253, 27
	v_readlane_b32 s68, v253, 28
	v_readlane_b32 s69, v253, 29
	v_readlane_b32 s70, v253, 30
	v_readlane_b32 s71, v253, 31
	v_readlane_b32 s72, v253, 32
	v_readlane_b32 s73, v253, 33
	s_branch .LBB0_311

; #define LAS __attribute__((address_space(3)))
; __device__ __forceinline__ void rwkv_scan_prompt(const Params& p, LAS unsigned char* lds, int bh, int rq) {
;     ...
;             const LAS float* ob = OPS + buf * TC * 6 * 64;
;             f32x4 r4 = *(const LAS f32x4*)(ob + cg_ * 4), d4 = *(const LAS f32x4*)(ob + 64 + cg_ * 4), k4 = *(const LAS f32x4*)(ob + 128 + cg_ * 4),
;                   a4 = *(const LAS f32x4*)(ob + 256 + cg_ * 4), b4 = *(const LAS f32x4*)(ob + 320 + cg_ * 4);
;             float vv = ob[192 + rq * 16 + rloc];
;             f32x4 rp = r4;
; #pragma unroll
;             for (int tk = 0; tk < TC; ++tk) {
;                 f32x4 nr4 = r4, nd4 = d4, nk4 = k4, na4 = a4, nb4 = b4; float nvv = vv;
;                 if (tk < TC - 1) {
;                     const LAS float* o = ob + (tk + 1) * 6 * 64;
;                     nr4 = *(const LAS f32x4*)(o + cg_ * 4); nd4 = *(const LAS f32x4*)(o + 64 + cg_ * 4); nk4 = *(const LAS f32x4*)(o + 128 + cg_ * 4);
;                     na4 = *(const LAS f32x4*)(o + 256 + cg_ * 4); nb4 = *(const LAS f32x4*)(o + 320 + cg_ * 4);
;                     nvv = o[192 + rq * 16 + rloc];
;                 }
;                 __builtin_amdgcn_sched_barrier(0);
;                 typedef float f32x2_ __attribute__((ext_vector_type(2)));
;                 f32x2_ ta = (f32x2_){S[0], S[1]} * (f32x2_){a4[0], a4[1]}; ta = (f32x2_){S[2], S[3]} * (f32x2_){a4[2], a4[3]} + ta;
;                 f32x2_ ty = (f32x2_){S[0], S[1]} * (f32x2_){rp[0], rp[1]}; ty = (f32x2_){S[2], S[3]} * (f32x2_){rp[2], rp[3]} + ty;
;                 const f32x4 T = S * d4 + vv * k4;
;                 float sa = ta[0] + ta[1];
;                 float yp = ty[0] + ty[1];
;                 sa = dpp_add<0xB1>(sa); yp = dpp_add<0xB1>(yp);
;                 sa = dpp_add<0x4E>(sa); yp = dpp_add<0x4E>(yp);
;                 sa = dpp_add<0x124>(sa); yp = dpp_add<0x124>(yp);
;                 sa = dpp_add<0x128>(sa); yp = dpp_add<0x128>(yp);
;                 if (tk > 0) yk[(tk - 1) >> 4] = (cg_ == ((tk - 1) & 15)) ? yp : yk[(tk - 1) >> 4];
;                 S = sa * b4 + T;
;                 rp = r4;
;                 r4 = nr4; d4 = nd4; k4 = nk4; a4 = na4; b4 = nb4; vv = nvv;
.LBB0_336:
	s_and_b32 s95, s73, 1
	s_and_saveexec_b64 s[74:75], s[38:39]
	s_xor_b64 s[74:75], exec, s[74:75]
	s_cbranch_execz .LBB0_338
	s_mul_i32 s78, s95, 0xc000
	s_add_i32 s78, s78, 0
	v_lshl_add_u32 v28, v36, 2, s78
	v_lshl_add_u32 v29, v154, 2, s78
	ds_read_b128 v[30:33], v28
	ds_read_b128 v[160:163], v28 offset:256
	ds_read_b128 v[164:167], v28 offset:512
	ds_read_b128 v[168:171], v28 offset:1024
	ds_read2st64_b32 v[34:35], v29 offset0:3 offset1:9
	ds_read_b128 v[172:175], v28 offset:1280
	ds_read_b128 v[176:179], v28 offset:1536
	ds_read_b128 v[180:183], v28 offset:1792
	ds_read_b128 v[184:187], v28 offset:2048
	ds_read_b128 v[188:191], v28 offset:2560
	ds_read_b128 v[192:195], v28 offset:2816
	s_waitcnt lgkmcnt(7)
	v_pk_mul_f32 v[170:171], v[26:27], v[170:171]
	s_waitcnt lgkmcnt(6)
	v_pk_mul_f32 v[164:165], v[164:165], v[34:35] op_sel_hi:[1,0]
	v_pk_fma_f32 v[168:169], v[24:25], v[168:169], v[170:171]
	v_pk_mul_f32 v[166:167], v[166:167], v[34:35] op_sel_hi:[1,0]
	v_add_f32_e32 v168, v168, v169
	v_pk_fma_f32 v[26:27], v[26:27], v[162:163], v[166:167]
	v_pk_fma_f32 v[24:25], v[24:25], v[160:161], v[164:165]
	v_add_f32_dpp v168, v168, v168 quad_perm:[1,0,3,2] row_mask:0xf bank_mask:0xf bound_ctrl:1
	s_nop 1
	v_add_f32_dpp v168, v168, v168 quad_perm:[2,3,0,1] row_mask:0xf bank_mask:0xf bound_ctrl:1
	s_nop 1
	v_add_f32_dpp v168, v168, v168 row_ror:4 row_mask:0xf bank_mask:0xf bound_ctrl:1
	s_nop 1
	v_add_f32_dpp v168, v168, v168 row_ror:8 row_mask:0xf bank_mask:0xf bound_ctrl:1
	s_waitcnt lgkmcnt(5)
	v_pk_fma_f32 v[196:197], v[172:173], v[168:169], v[24:25] op_sel_hi:[1,0,1]
	v_pk_fma_f32 v[198:199], v[174:175], v[168:169], v[26:27] op_sel_hi:[1,0,1]
	ds_read_b128 v[24:27], v28 offset:3072
	ds_read_b128 v[160:163], v28 offset:3328
	ds_read_b128 v[164:167], v28 offset:3584
	ds_read_b128 v[168:171], v28 offset:4096
	ds_read_b128 v[172:175], v28 offset:4352
	ds_read_b32 v34, v29 offset:3840
	s_waitcnt lgkmcnt(7)
	v_pk_mul_f32 v[190:191], v[190:191], v[198:199]
	v_pk_mul_f32 v[32:33], v[32:33], v[198:199]
	v_pk_fma_f32 v[188:189], v[188:189], v[196:197], v[190:191]
	v_pk_fma_f32 v[30:31], v[30:31], v[196:197], v[32:33]
	v_pk_mul_f32 v[32:33], v[180:181], v[196:197]
	v_add_f32_e32 v206, v188, v189
	v_pk_mul_f32 v[180:181], v[182:183], v[198:199]
	v_add_f32_e32 v30, v30, v31
	v_add_f32_dpp v31, v206, v206 quad_perm:[1,0,3,2] row_mask:0xf bank_mask:0xf bound_ctrl:1
	v_mov_b32_e32 v182, v35
	v_add_f32_dpp v30, v30, v30 quad_perm:[1,0,3,2] row_mask:0xf bank_mask:0xf bound_ctrl:1
	v_add_f32_dpp v31, v31, v31 quad_perm:[2,3,0,1] row_mask:0xf bank_mask:0xf bound_ctrl:1
	v_pk_fma_f32 v[180:181], v[186:187], v[182:183], v[180:181] op_sel_hi:[1,0,1]
	v_add_f32_dpp v30, v30, v30 quad_perm:[2,3,0,1] row_mask:0xf bank_mask:0xf bound_ctrl:1
	v_add_f32_dpp v31, v31, v31 row_ror:4 row_mask:0xf bank_mask:0xf bound_ctrl:1
	v_pk_fma_f32 v[32:33], v[184:185], v[182:183], v[32:33] op_sel_hi:[1,0,1]
	v_add_f32_dpp v35, v30, v30 row_ror:4 row_mask:0xf bank_mask:0xf bound_ctrl:1
	v_add_f32_dpp v30, v31, v31 row_ror:8 row_mask:0xf bank_mask:0xf bound_ctrl:1
	s_waitcnt lgkmcnt(6)
	v_pk_fma_f32 v[196:197], v[192:193], v[30:31], v[32:33] op_sel_hi:[1,0,1]
	v_add_f32_dpp v207, v35, v35 row_ror:8 row_mask:0xf bank_mask:0x1 bound_ctrl:1
	v_pk_fma_f32 v[198:199], v[194:195], v[30:31], v[180:181] op_sel_hi:[1,0,1]
	ds_read_b128 v[30:33], v28 offset:4608
	ds_read_b128 v[180:183], v28 offset:4864
	ds_read_b128 v[184:187], v28 offset:5120
	ds_read_b128 v[188:191], v28 offset:5632
	ds_read_b128 v[192:195], v28 offset:5888
	ds_read_b32 v200, v29 offset:5376
	s_waitcnt lgkmcnt(8)
	v_pk_mul_f32 v[170:171], v[170:171], v[198:199]
	v_pk_mul_f32 v[160:161], v[160:161], v[196:197]
	v_pk_fma_f32 v[168:169], v[168:169], v[196:197], v[170:171]
	v_pk_mul_f32 v[170:171], v[178:179], v[198:199]
	v_pk_mul_f32 v[162:163], v[162:163], v[198:199]
	v_pk_fma_f32 v[170:171], v[176:177], v[196:197], v[170:171]
	s_waitcnt lgkmcnt(6)
	v_pk_fma_f32 v[162:163], v[166:167], v[34:35], v[162:163] op_sel_hi:[1,0,1]
	v_add_f32_e32 v206, v168, v169
	v_pk_fma_f32 v[34:35], v[164:165], v[34:35], v[160:161] op_sel_hi:[1,0,1]
	v_add_f32_e32 v161, v170, v171
	v_add_f32_dpp v160, v206, v206 quad_perm:[1,0,3,2] row_mask:0xf bank_mask:0xf bound_ctrl:1
	s_nop 0
	v_add_f32_dpp v161, v161, v161 quad_perm:[1,0,3,2] row_mask:0xf bank_mask:0xf bound_ctrl:1
	v_add_f32_dpp v160, v160, v160 quad_perm:[2,3,0,1] row_mask:0xf bank_mask:0xf bound_ctrl:1
	s_nop 0
	v_add_f32_dpp v161, v161, v161 quad_perm:[2,3,0,1] row_mask:0xf bank_mask:0xf bound_ctrl:1
	v_add_f32_dpp v160, v160, v160 row_ror:4 row_mask:0xf bank_mask:0xf bound_ctrl:1
	s_nop 0
	v_add_f32_dpp v161, v161, v161 row_ror:4 row_mask:0xf bank_mask:0xf bound_ctrl:1
	v_add_f32_dpp v160, v160, v160 row_ror:8 row_mask:0xf bank_mask:0xf bound_ctrl:1
	v_pk_fma_f32 v[34:35], v[172:173], v[160:161], v[34:35] op_sel_hi:[1,0,1]
	v_add_f32_dpp v208, v161, v161 row_ror:8 row_mask:0xf bank_mask:0x1 bound_ctrl:1
	v_pk_fma_f32 v[196:197], v[174:175], v[160:161], v[162:163] op_sel_hi:[1,0,1]
	ds_read_b128 v[160:163], v28 offset:6144
	ds_read_b128 v[164:167], v28 offset:6400
	ds_read_b128 v[168:171], v28 offset:6656
	ds_read_b128 v[172:175], v28 offset:7168
	ds_read_b128 v[176:179], v28 offset:7424
	ds_read_b32 v198, v29 offset:6912
	s_waitcnt lgkmcnt(8)
	v_pk_mul_f32 v[190:191], v[190:191], v[196:197]
	v_pk_mul_f32 v[26:27], v[26:27], v[196:197]
	v_pk_fma_f32 v[188:189], v[188:189], v[34:35], v[190:191]
	v_pk_fma_f32 v[24:25], v[24:25], v[34:35], v[26:27]
	v_add_f32_e32 v206, v188, v189
	v_pk_mul_f32 v[26:27], v[180:181], v[34:35]
	v_add_f32_e32 v24, v24, v25
	v_add_f32_dpp v25, v206, v206 quad_perm:[1,0,3,2] row_mask:0xf bank_mask:0xf bound_ctrl:1
	v_pk_mul_f32 v[34:35], v[182:183], v[196:197]
	v_add_f32_dpp v24, v24, v24 quad_perm:[1,0,3,2] row_mask:0xf bank_mask:0xf bound_ctrl:1
	s_waitcnt lgkmcnt(6)
; #define LAS __attribute__((address_space(3)))
; __device__ __forceinline__ void rwkv_scan_prompt(const Params& p, LAS unsigned char* lds, int bh, int rq) {
;     ...
;             for (int tk = 0; tk < TC; ++tk) {
;                 f32x4 nr4 = r4, nd4 = d4, nk4 = k4, na4 = a4, nb4 = b4; float nvv = vv;
;                 if (tk < TC - 1) {
;                     const LAS float* o = ob + (tk + 1) * 6 * 64;
;                     nr4 = *(const LAS f32x4*)(o + cg_ * 4); nd4 = *(const LAS f32x4*)(o + 64 + cg_ * 4); nk4 = *(const LAS f32x4*)(o + 128 + cg_ * 4);
;                     na4 = *(const LAS f32x4*)(o + 256 + cg_ * 4); nb4 = *(const LAS f32x4*)(o + 320 + cg_ * 4);
;                     nvv = o[192 + rq * 16 + rloc];
;                 }
;                 __builtin_amdgcn_sched_barrier(0);
;                 typedef float f32x2_ __attribute__((ext_vector_type(2)));
;                 f32x2_ ta = (f32x2_){S[0], S[1]} * (f32x2_){a4[0], a4[1]}; ta = (f32x2_){S[2], S[3]} * (f32x2_){a4[2], a4[3]} + ta;
;                 f32x2_ ty = (f32x2_){S[0], S[1]} * (f32x2_){rp[0], rp[1]}; ty = (f32x2_){S[2], S[3]} * (f32x2_){rp[2], rp[3]} + ty;
;                 const f32x4 T = S * d4 + vv * k4;
;                 float sa = ta[0] + ta[1];
;                 float yp = ty[0] + ty[1];
;                 sa = dpp_add<0xB1>(sa); yp = dpp_add<0xB1>(yp);
;                 sa = dpp_add<0x4E>(sa); yp = dpp_add<0x4E>(yp);
;                 sa = dpp_add<0x124>(sa); yp = dpp_add<0x124>(yp);
;                 sa = dpp_add<0x128>(sa); yp = dpp_add<0x128>(yp);
;                 if (tk > 0) yk[(tk - 1) >> 4] = (cg_ == ((tk - 1) & 15)) ? yp : yk[(tk - 1) >> 4];
;                 S = sa * b4 + T;
;                 rp = r4;
;                 r4 = nr4; d4 = nd4; k4 = nk4; a4 = na4; b4 = nb4; vv = nvv;
	v_add_f32_dpp v25, v25, v25 quad_perm:[2,3,0,1] row_mask:0xf bank_mask:0xf bound_ctrl:1
	v_pk_fma_f32 v[34:35], v[186:187], v[200:201], v[34:35] op_sel_hi:[1,0,1]
	v_add_f32_dpp v24, v24, v24 quad_perm:[2,3,0,1] row_mask:0xf bank_mask:0xf bound_ctrl:1
	v_add_f32_dpp v25, v25, v25 row_ror:4 row_mask:0xf bank_mask:0xf bound_ctrl:1
	v_pk_fma_f32 v[26:27], v[184:185], v[200:201], v[26:27] op_sel_hi:[1,0,1]
	v_add_f32_dpp v180, v24, v24 row_ror:4 row_mask:0xf bank_mask:0xf bound_ctrl:1
	v_add_f32_dpp v24, v25, v25 row_ror:8 row_mask:0xf bank_mask:0xf bound_ctrl:1
	v_pk_fma_f32 v[196:197], v[192:193], v[24:25], v[26:27] op_sel_hi:[1,0,1]
	v_add_f32_dpp v209, v180, v180 row_ror:8 row_mask:0xf bank_mask:0x1 bound_ctrl:1
	v_pk_fma_f32 v[34:35], v[194:195], v[24:25], v[34:35] op_sel_hi:[1,0,1]
	ds_read_b128 v[24:27], v28 offset:7680
	ds_read_b128 v[180:183], v28 offset:7936
	ds_read_b128 v[184:187], v28 offset:8192
	ds_read_b128 v[188:191], v28 offset:8704
	ds_read_b128 v[192:195], v28 offset:8960
	ds_read_b32 v200, v29 offset:8448
	s_waitcnt lgkmcnt(8)
	v_pk_mul_f32 v[174:175], v[174:175], v[34:35]
	v_pk_mul_f32 v[32:33], v[32:33], v[34:35]
	v_pk_fma_f32 v[172:173], v[172:173], v[196:197], v[174:175]
	v_pk_fma_f32 v[30:31], v[30:31], v[196:197], v[32:33]
	v_add_f32_e32 v206, v172, v173
	v_pk_mul_f32 v[32:33], v[164:165], v[196:197]
	v_add_f32_e32 v30, v30, v31
	v_add_f32_dpp v31, v206, v206 quad_perm:[1,0,3,2] row_mask:0xf bank_mask:0xf bound_ctrl:1
	v_pk_mul_f32 v[34:35], v[166:167], v[34:35]
	v_add_f32_dpp v30, v30, v30 quad_perm:[1,0,3,2] row_mask:0xf bank_mask:0xf bound_ctrl:1
	s_waitcnt lgkmcnt(6)
	v_add_f32_dpp v31, v31, v31 quad_perm:[2,3,0,1] row_mask:0xf bank_mask:0xf bound_ctrl:1
	v_pk_fma_f32 v[34:35], v[170:171], v[198:199], v[34:35] op_sel_hi:[1,0,1]
	v_add_f32_dpp v30, v30, v30 quad_perm:[2,3,0,1] row_mask:0xf bank_mask:0xf bound_ctrl:1
	v_add_f32_dpp v31, v31, v31 row_ror:4 row_mask:0xf bank_mask:0xf bound_ctrl:1
	v_pk_fma_f32 v[32:33], v[168:169], v[198:199], v[32:33] op_sel_hi:[1,0,1]
	v_add_f32_dpp v164, v30, v30 row_ror:4 row_mask:0xf bank_mask:0xf bound_ctrl:1
	v_add_f32_dpp v30, v31, v31 row_ror:8 row_mask:0xf bank_mask:0xf bound_ctrl:1
	v_pk_fma_f32 v[196:197], v[176:177], v[30:31], v[32:33] op_sel_hi:[1,0,1]
	v_add_f32_dpp v210, v164, v164 row_ror:8 row_mask:0xf bank_mask:0x1 bound_ctrl:1
	v_pk_fma_f32 v[34:35], v[178:179], v[30:31], v[34:35] op_sel_hi:[1,0,1]
	ds_read_b128 v[30:33], v28 offset:9216
	ds_read_b128 v[164:167], v28 offset:9472
	ds_read_b128 v[168:171], v28 offset:9728
	ds_read_b128 v[172:175], v28 offset:10240
	ds_read_b128 v[176:179], v28 offset:10496
	ds_read_b32 v198, v29 offset:9984
	s_waitcnt lgkmcnt(8)
	v_pk_mul_f32 v[190:191], v[190:191], v[34:35]
	v_pk_mul_f32 v[162:163], v[162:163], v[34:35]
	v_pk_fma_f32 v[188:189], v[188:189], v[196:197], v[190:191]
	v_pk_fma_f32 v[160:161], v[160:161], v[196:197], v[162:163]
	v_add_f32_e32 v206, v188, v189
	v_pk_mul_f32 v[162:163], v[180:181], v[196:197]
	v_add_f32_e32 v160, v160, v161
	v_add_f32_dpp v161, v206, v206 quad_perm:[1,0,3,2] row_mask:0xf bank_mask:0xf bound_ctrl:1
	v_pk_mul_f32 v[34:35], v[182:183], v[34:35]
	v_add_f32_dpp v160, v160, v160 quad_perm:[1,0,3,2] row_mask:0xf bank_mask:0xf bound_ctrl:1
	s_waitcnt lgkmcnt(6)
	v_add_f32_dpp v161, v161, v161 quad_perm:[2,3,0,1] row_mask:0xf bank_mask:0xf bound_ctrl:1
	v_pk_fma_f32 v[34:35], v[186:187], v[200:201], v[34:35] op_sel_hi:[1,0,1]
	v_add_f32_dpp v160, v160, v160 quad_perm:[2,3,0,1] row_mask:0xf bank_mask:0xf bound_ctrl:1
	v_add_f32_dpp v161, v161, v161 row_ror:4 row_mask:0xf bank_mask:0xf bound_ctrl:1
	v_pk_fma_f32 v[162:163], v[184:185], v[200:201], v[162:163] op_sel_hi:[1,0,1]
	v_add_f32_dpp v180, v160, v160 row_ror:4 row_mask:0xf bank_mask:0xf bound_ctrl:1
	v_add_f32_dpp v160, v161, v161 row_ror:8 row_mask:0xf bank_mask:0xf bound_ctrl:1
	v_pk_fma_f32 v[196:197], v[192:193], v[160:161], v[162:163] op_sel_hi:[1,0,1]
	v_add_f32_dpp v207, v180, v180 row_ror:8 row_mask:0xf bank_mask:0x2 bound_ctrl:1
	v_pk_fma_f32 v[34:35], v[194:195], v[160:161], v[34:35] op_sel_hi:[1,0,1]
	ds_read_b128 v[160:163], v28 offset:10752
	ds_read_b128 v[180:183], v28 offset:11008
	ds_read_b128 v[184:187], v28 offset:11264
	ds_read_b128 v[188:191], v28 offset:11776
	ds_read_b128 v[192:195], v28 offset:12032
	ds_read_b32 v200, v29 offset:11520
	s_waitcnt lgkmcnt(8)
	v_pk_mul_f32 v[174:175], v[174:175], v[34:35]
	v_pk_mul_f32 v[26:27], v[26:27], v[34:35]
	v_pk_fma_f32 v[172:173], v[172:173], v[196:197], v[174:175]
	v_pk_fma_f32 v[24:25], v[24:25], v[196:197], v[26:27]
	v_add_f32_e32 v206, v172, v173
	v_pk_mul_f32 v[26:27], v[164:165], v[196:197]
	v_add_f32_e32 v24, v24, v25
	v_add_f32_dpp v25, v206, v206 quad_perm:[1,0,3,2] row_mask:0xf bank_mask:0xf bound_ctrl:1
	v_pk_mul_f32 v[34:35], v[166:167], v[34:35]
	v_add_f32_dpp v24, v24, v24 quad_perm:[1,0,3,2] row_mask:0xf bank_mask:0xf bound_ctrl:1
	s_waitcnt lgkmcnt(6)
	v_add_f32_dpp v25, v25, v25 quad_perm:[2,3,0,1] row_mask:0xf bank_mask:0xf bound_ctrl:1
	v_pk_fma_f32 v[34:35], v[170:171], v[198:199], v[34:35] op_sel_hi:[1,0,1]
	v_add_f32_dpp v24, v24, v24 quad_perm:[2,3,0,1] row_mask:0xf bank_mask:0xf bound_ctrl:1
	v_add_f32_dpp v25, v25, v25 row_ror:4 row_mask:0xf bank_mask:0xf bound_ctrl:1
	v_pk_fma_f32 v[26:27], v[168:169], v[198:199], v[26:27] op_sel_hi:[1,0,1]
	v_add_f32_dpp v164, v24, v24 row_ror:4 row_mask:0xf bank_mask:0xf bound_ctrl:1
	v_add_f32_dpp v24, v25, v25 row_ror:8 row_mask:0xf bank_mask:0xf bound_ctrl:1
	v_pk_fma_f32 v[196:197], v[176:177], v[24:25], v[26:27] op_sel_hi:[1,0,1]
	v_add_f32_dpp v208, v164, v164 row_ror:8 row_mask:0xf bank_mask:0x2 bound_ctrl:1
	v_pk_fma_f32 v[34:35], v[178:179], v[24:25], v[34:35] op_sel_hi:[1,0,1]
	ds_read_b128 v[24:27], v28 offset:12288
	ds_read_b128 v[164:167], v28 offset:12544
	ds_read_b128 v[168:171], v28 offset:12800
	ds_read_b128 v[172:175], v28 offset:13312
	ds_read_b128 v[176:179], v28 offset:13568
	ds_read_b32 v198, v29 offset:13056
	s_waitcnt lgkmcnt(8)
; #define LAS __attribute__((address_space(3)))
; __device__ __forceinline__ void rwkv_scan_prompt(const Params& p, LAS unsigned char* lds, int bh, int rq) {
;     ...
;             for (int tk = 0; tk < TC; ++tk) {
;                 f32x4 nr4 = r4, nd4 = d4, nk4 = k4, na4 = a4, nb4 = b4; float nvv = vv;
;                 if (tk < TC - 1) {
;                     const LAS float* o = ob + (tk + 1) * 6 * 64;
;                     nr4 = *(const LAS f32x4*)(o + cg_ * 4); nd4 = *(const LAS f32x4*)(o + 64 + cg_ * 4); nk4 = *(const LAS f32x4*)(o + 128 + cg_ * 4);
;                     na4 = *(const LAS f32x4*)(o + 256 + cg_ * 4); nb4 = *(const LAS f32x4*)(o + 320 + cg_ * 4);
;                     nvv = o[192 + rq * 16 + rloc];
;                 }
;                 __builtin_amdgcn_sched_barrier(0);
;                 typedef float f32x2_ __attribute__((ext_vector_type(2)));
;                 f32x2_ ta = (f32x2_){S[0], S[1]} * (f32x2_){a4[0], a4[1]}; ta = (f32x2_){S[2], S[3]} * (f32x2_){a4[2], a4[3]} + ta;
;                 f32x2_ ty = (f32x2_){S[0], S[1]} * (f32x2_){rp[0], rp[1]}; ty = (f32x2_){S[2], S[3]} * (f32x2_){rp[2], rp[3]} + ty;
;                 const f32x4 T = S * d4 + vv * k4;
;                 float sa = ta[0] + ta[1];
;                 float yp = ty[0] + ty[1];
;                 sa = dpp_add<0xB1>(sa); yp = dpp_add<0xB1>(yp);
;                 sa = dpp_add<0x4E>(sa); yp = dpp_add<0x4E>(yp);
;                 sa = dpp_add<0x124>(sa); yp = dpp_add<0x124>(yp);
;                 sa = dpp_add<0x128>(sa); yp = dpp_add<0x128>(yp);
;                 if (tk > 0) yk[(tk - 1) >> 4] = (cg_ == ((tk - 1) & 15)) ? yp : yk[(tk - 1) >> 4];
;                 S = sa * b4 + T;
;                 rp = r4;
;                 r4 = nr4; d4 = nd4; k4 = nk4; a4 = na4; b4 = nb4; vv = nvv;
	v_pk_mul_f32 v[190:191], v[190:191], v[34:35]
	v_pk_mul_f32 v[32:33], v[32:33], v[34:35]
	v_pk_fma_f32 v[188:189], v[188:189], v[196:197], v[190:191]
	v_pk_fma_f32 v[30:31], v[30:31], v[196:197], v[32:33]
	v_add_f32_e32 v206, v188, v189
	v_pk_mul_f32 v[32:33], v[180:181], v[196:197]
	v_add_f32_e32 v30, v30, v31
	v_add_f32_dpp v31, v206, v206 quad_perm:[1,0,3,2] row_mask:0xf bank_mask:0xf bound_ctrl:1
	v_pk_mul_f32 v[34:35], v[182:183], v[34:35]
	v_add_f32_dpp v30, v30, v30 quad_perm:[1,0,3,2] row_mask:0xf bank_mask:0xf bound_ctrl:1
	s_waitcnt lgkmcnt(6)
	v_add_f32_dpp v31, v31, v31 quad_perm:[2,3,0,1] row_mask:0xf bank_mask:0xf bound_ctrl:1
	v_pk_fma_f32 v[34:35], v[186:187], v[200:201], v[34:35] op_sel_hi:[1,0,1]
	v_add_f32_dpp v30, v30, v30 quad_perm:[2,3,0,1] row_mask:0xf bank_mask:0xf bound_ctrl:1
	v_add_f32_dpp v31, v31, v31 row_ror:4 row_mask:0xf bank_mask:0xf bound_ctrl:1
	v_pk_fma_f32 v[32:33], v[184:185], v[200:201], v[32:33] op_sel_hi:[1,0,1]
	v_add_f32_dpp v180, v30, v30 row_ror:4 row_mask:0xf bank_mask:0xf bound_ctrl:1
	v_add_f32_dpp v30, v31, v31 row_ror:8 row_mask:0xf bank_mask:0xf bound_ctrl:1
	v_pk_fma_f32 v[196:197], v[192:193], v[30:31], v[32:33] op_sel_hi:[1,0,1]
	v_add_f32_dpp v209, v180, v180 row_ror:8 row_mask:0xf bank_mask:0x2 bound_ctrl:1
	v_pk_fma_f32 v[34:35], v[194:195], v[30:31], v[34:35] op_sel_hi:[1,0,1]
	ds_read_b128 v[30:33], v28 offset:13824
	ds_read_b128 v[180:183], v28 offset:14080
	ds_read_b128 v[184:187], v28 offset:14336
	ds_read_b128 v[188:191], v28 offset:14848
	ds_read_b128 v[192:195], v28 offset:15104
	ds_read_b32 v200, v29 offset:14592
	s_waitcnt lgkmcnt(8)
	v_pk_mul_f32 v[174:175], v[174:175], v[34:35]
	v_pk_mul_f32 v[162:163], v[162:163], v[34:35]
	v_pk_fma_f32 v[172:173], v[172:173], v[196:197], v[174:175]
	v_pk_fma_f32 v[160:161], v[160:161], v[196:197], v[162:163]
	v_add_f32_e32 v206, v172, v173
	v_pk_mul_f32 v[162:163], v[164:165], v[196:197]
	v_add_f32_e32 v160, v160, v161
	v_add_f32_dpp v161, v206, v206 quad_perm:[1,0,3,2] row_mask:0xf bank_mask:0xf bound_ctrl:1
	v_pk_mul_f32 v[34:35], v[166:167], v[34:35]
	v_add_f32_dpp v160, v160, v160 quad_perm:[1,0,3,2] row_mask:0xf bank_mask:0xf bound_ctrl:1
	s_waitcnt lgkmcnt(6)
	v_add_f32_dpp v161, v161, v161 quad_perm:[2,3,0,1] row_mask:0xf bank_mask:0xf bound_ctrl:1
	v_pk_fma_f32 v[34:35], v[170:171], v[198:199], v[34:35] op_sel_hi:[1,0,1]
	v_add_f32_dpp v160, v160, v160 quad_perm:[2,3,0,1] row_mask:0xf bank_mask:0xf bound_ctrl:1
	v_add_f32_dpp v161, v161, v161 row_ror:4 row_mask:0xf bank_mask:0xf bound_ctrl:1
	v_pk_fma_f32 v[162:163], v[168:169], v[198:199], v[162:163] op_sel_hi:[1,0,1]
	v_add_f32_dpp v164, v160, v160 row_ror:4 row_mask:0xf bank_mask:0xf bound_ctrl:1
	v_add_f32_dpp v160, v161, v161 row_ror:8 row_mask:0xf bank_mask:0xf bound_ctrl:1
	v_pk_fma_f32 v[196:197], v[176:177], v[160:161], v[162:163] op_sel_hi:[1,0,1]
	v_add_f32_dpp v210, v164, v164 row_ror:8 row_mask:0xf bank_mask:0x2 bound_ctrl:1
	v_pk_fma_f32 v[34:35], v[178:179], v[160:161], v[34:35] op_sel_hi:[1,0,1]
	ds_read_b128 v[160:163], v28 offset:15360
	ds_read_b128 v[164:167], v28 offset:15616
	ds_read_b128 v[168:171], v28 offset:15872
	ds_read_b128 v[172:175], v28 offset:16384
	ds_read_b128 v[176:179], v28 offset:16640
	ds_read_b32 v198, v29 offset:16128
	s_waitcnt lgkmcnt(8)
	v_pk_mul_f32 v[190:191], v[190:191], v[34:35]
	v_pk_mul_f32 v[26:27], v[26:27], v[34:35]
	v_pk_fma_f32 v[188:189], v[188:189], v[196:197], v[190:191]
	v_pk_fma_f32 v[24:25], v[24:25], v[196:197], v[26:27]
	v_add_f32_e32 v206, v188, v189
	v_pk_mul_f32 v[26:27], v[180:181], v[196:197]
	v_add_f32_e32 v24, v24, v25
	v_add_f32_dpp v25, v206, v206 quad_perm:[1,0,3,2] row_mask:0xf bank_mask:0xf bound_ctrl:1
	v_pk_mul_f32 v[34:35], v[182:183], v[34:35]
	v_add_f32_dpp v24, v24, v24 quad_perm:[1,0,3,2] row_mask:0xf bank_mask:0xf bound_ctrl:1
	s_waitcnt lgkmcnt(6)
	v_add_f32_dpp v25, v25, v25 quad_perm:[2,3,0,1] row_mask:0xf bank_mask:0xf bound_ctrl:1
	v_pk_fma_f32 v[34:35], v[186:187], v[200:201], v[34:35] op_sel_hi:[1,0,1]
	v_add_f32_dpp v24, v24, v24 quad_perm:[2,3,0,1] row_mask:0xf bank_mask:0xf bound_ctrl:1
	v_add_f32_dpp v25, v25, v25 row_ror:4 row_mask:0xf bank_mask:0xf bound_ctrl:1
	v_pk_fma_f32 v[26:27], v[184:185], v[200:201], v[26:27] op_sel_hi:[1,0,1]
	v_add_f32_dpp v180, v24, v24 row_ror:4 row_mask:0xf bank_mask:0xf bound_ctrl:1
	v_add_f32_dpp v24, v25, v25 row_ror:8 row_mask:0xf bank_mask:0xf bound_ctrl:1
	v_pk_fma_f32 v[196:197], v[192:193], v[24:25], v[26:27] op_sel_hi:[1,0,1]
	v_add_f32_dpp v207, v180, v180 row_ror:8 row_mask:0xf bank_mask:0x4 bound_ctrl:1
	v_pk_fma_f32 v[34:35], v[194:195], v[24:25], v[34:35] op_sel_hi:[1,0,1]
	ds_read_b128 v[24:27], v28 offset:16896
	ds_read_b128 v[180:183], v28 offset:17152
	ds_read_b128 v[184:187], v28 offset:17408
	ds_read_b128 v[188:191], v28 offset:17920
	ds_read_b128 v[192:195], v28 offset:18176
	ds_read_b32 v200, v29 offset:17664
	s_waitcnt lgkmcnt(8)
	v_pk_mul_f32 v[174:175], v[174:175], v[34:35]
	v_pk_mul_f32 v[32:33], v[32:33], v[34:35]
	v_pk_fma_f32 v[172:173], v[172:173], v[196:197], v[174:175]
	v_pk_fma_f32 v[30:31], v[30:31], v[196:197], v[32:33]
	v_add_f32_e32 v206, v172, v173
	v_pk_mul_f32 v[32:33], v[164:165], v[196:197]
	v_add_f32_e32 v30, v30, v31
	v_add_f32_dpp v31, v206, v206 quad_perm:[1,0,3,2] row_mask:0xf bank_mask:0xf bound_ctrl:1
	v_pk_mul_f32 v[34:35], v[166:167], v[34:35]
	v_add_f32_dpp v30, v30, v30 quad_perm:[1,0,3,2] row_mask:0xf bank_mask:0xf bound_ctrl:1
	s_waitcnt lgkmcnt(6)
; #define LAS __attribute__((address_space(3)))
; __device__ __forceinline__ void rwkv_scan_prompt(const Params& p, LAS unsigned char* lds, int bh, int rq) {
;     ...
;             for (int tk = 0; tk < TC; ++tk) {
;                 f32x4 nr4 = r4, nd4 = d4, nk4 = k4, na4 = a4, nb4 = b4; float nvv = vv;
;                 if (tk < TC - 1) {
;                     const LAS float* o = ob + (tk + 1) * 6 * 64;
;                     nr4 = *(const LAS f32x4*)(o + cg_ * 4); nd4 = *(const LAS f32x4*)(o + 64 + cg_ * 4); nk4 = *(const LAS f32x4*)(o + 128 + cg_ * 4);
;                     na4 = *(const LAS f32x4*)(o + 256 + cg_ * 4); nb4 = *(const LAS f32x4*)(o + 320 + cg_ * 4);
;                     nvv = o[192 + rq * 16 + rloc];
;                 }
;                 __builtin_amdgcn_sched_barrier(0);
;                 typedef float f32x2_ __attribute__((ext_vector_type(2)));
;                 f32x2_ ta = (f32x2_){S[0], S[1]} * (f32x2_){a4[0], a4[1]}; ta = (f32x2_){S[2], S[3]} * (f32x2_){a4[2], a4[3]} + ta;
;                 f32x2_ ty = (f32x2_){S[0], S[1]} * (f32x2_){rp[0], rp[1]}; ty = (f32x2_){S[2], S[3]} * (f32x2_){rp[2], rp[3]} + ty;
;                 const f32x4 T = S * d4 + vv * k4;
;                 float sa = ta[0] + ta[1];
;                 float yp = ty[0] + ty[1];
;                 sa = dpp_add<0xB1>(sa); yp = dpp_add<0xB1>(yp);
;                 sa = dpp_add<0x4E>(sa); yp = dpp_add<0x4E>(yp);
;                 sa = dpp_add<0x124>(sa); yp = dpp_add<0x124>(yp);
;                 sa = dpp_add<0x128>(sa); yp = dpp_add<0x128>(yp);
;                 if (tk > 0) yk[(tk - 1) >> 4] = (cg_ == ((tk - 1) & 15)) ? yp : yk[(tk - 1) >> 4];
;                 S = sa * b4 + T;
;                 rp = r4;
;                 r4 = nr4; d4 = nd4; k4 = nk4; a4 = na4; b4 = nb4; vv = nvv;
	v_add_f32_dpp v31, v31, v31 quad_perm:[2,3,0,1] row_mask:0xf bank_mask:0xf bound_ctrl:1
	v_pk_fma_f32 v[34:35], v[170:171], v[198:199], v[34:35] op_sel_hi:[1,0,1]
	v_add_f32_dpp v30, v30, v30 quad_perm:[2,3,0,1] row_mask:0xf bank_mask:0xf bound_ctrl:1
	v_add_f32_dpp v31, v31, v31 row_ror:4 row_mask:0xf bank_mask:0xf bound_ctrl:1
	v_pk_fma_f32 v[32:33], v[168:169], v[198:199], v[32:33] op_sel_hi:[1,0,1]
	v_add_f32_dpp v164, v30, v30 row_ror:4 row_mask:0xf bank_mask:0xf bound_ctrl:1
	v_add_f32_dpp v30, v31, v31 row_ror:8 row_mask:0xf bank_mask:0xf bound_ctrl:1
	v_pk_fma_f32 v[196:197], v[176:177], v[30:31], v[32:33] op_sel_hi:[1,0,1]
	v_add_f32_dpp v208, v164, v164 row_ror:8 row_mask:0xf bank_mask:0x4 bound_ctrl:1
	v_pk_fma_f32 v[34:35], v[178:179], v[30:31], v[34:35] op_sel_hi:[1,0,1]
	ds_read_b128 v[30:33], v28 offset:18432
	ds_read_b128 v[164:167], v28 offset:18688
	ds_read_b128 v[168:171], v28 offset:18944
	ds_read_b128 v[172:175], v28 offset:19456
	ds_read_b128 v[176:179], v28 offset:19712
	ds_read_b32 v198, v29 offset:19200
	s_waitcnt lgkmcnt(8)
	v_pk_mul_f32 v[190:191], v[190:191], v[34:35]
	v_pk_mul_f32 v[162:163], v[162:163], v[34:35]
	v_pk_fma_f32 v[188:189], v[188:189], v[196:197], v[190:191]
	v_pk_fma_f32 v[160:161], v[160:161], v[196:197], v[162:163]
	v_add_f32_e32 v206, v188, v189
	v_pk_mul_f32 v[162:163], v[180:181], v[196:197]
	v_add_f32_e32 v160, v160, v161
	v_add_f32_dpp v161, v206, v206 quad_perm:[1,0,3,2] row_mask:0xf bank_mask:0xf bound_ctrl:1
	v_pk_mul_f32 v[34:35], v[182:183], v[34:35]
	v_add_f32_dpp v160, v160, v160 quad_perm:[1,0,3,2] row_mask:0xf bank_mask:0xf bound_ctrl:1
	s_waitcnt lgkmcnt(6)
	v_add_f32_dpp v161, v161, v161 quad_perm:[2,3,0,1] row_mask:0xf bank_mask:0xf bound_ctrl:1
	v_pk_fma_f32 v[34:35], v[186:187], v[200:201], v[34:35] op_sel_hi:[1,0,1]
	v_add_f32_dpp v160, v160, v160 quad_perm:[2,3,0,1] row_mask:0xf bank_mask:0xf bound_ctrl:1
	v_add_f32_dpp v161, v161, v161 row_ror:4 row_mask:0xf bank_mask:0xf bound_ctrl:1
	v_pk_fma_f32 v[162:163], v[184:185], v[200:201], v[162:163] op_sel_hi:[1,0,1]
	v_add_f32_dpp v180, v160, v160 row_ror:4 row_mask:0xf bank_mask:0xf bound_ctrl:1
	v_add_f32_dpp v160, v161, v161 row_ror:8 row_mask:0xf bank_mask:0xf bound_ctrl:1
	v_pk_fma_f32 v[196:197], v[192:193], v[160:161], v[162:163] op_sel_hi:[1,0,1]
	v_add_f32_dpp v209, v180, v180 row_ror:8 row_mask:0xf bank_mask:0x4 bound_ctrl:1
	v_pk_fma_f32 v[34:35], v[194:195], v[160:161], v[34:35] op_sel_hi:[1,0,1]
	ds_read_b128 v[160:163], v28 offset:19968
	ds_read_b128 v[180:183], v28 offset:20224
	ds_read_b128 v[184:187], v28 offset:20480
	ds_read_b128 v[188:191], v28 offset:20992
	ds_read_b128 v[192:195], v28 offset:21248
	ds_read_b32 v200, v29 offset:20736
	s_waitcnt lgkmcnt(8)
	v_pk_mul_f32 v[174:175], v[174:175], v[34:35]
	v_pk_mul_f32 v[26:27], v[26:27], v[34:35]
	v_pk_fma_f32 v[172:173], v[172:173], v[196:197], v[174:175]
	v_pk_fma_f32 v[24:25], v[24:25], v[196:197], v[26:27]
	v_add_f32_e32 v206, v172, v173
	v_pk_mul_f32 v[26:27], v[164:165], v[196:197]
	v_add_f32_e32 v24, v24, v25
	v_add_f32_dpp v25, v206, v206 quad_perm:[1,0,3,2] row_mask:0xf bank_mask:0xf bound_ctrl:1
	v_pk_mul_f32 v[34:35], v[166:167], v[34:35]
	v_add_f32_dpp v24, v24, v24 quad_perm:[1,0,3,2] row_mask:0xf bank_mask:0xf bound_ctrl:1
	s_waitcnt lgkmcnt(6)
	v_add_f32_dpp v25, v25, v25 quad_perm:[2,3,0,1] row_mask:0xf bank_mask:0xf bound_ctrl:1
	v_pk_fma_f32 v[34:35], v[170:171], v[198:199], v[34:35] op_sel_hi:[1,0,1]
	v_add_f32_dpp v24, v24, v24 quad_perm:[2,3,0,1] row_mask:0xf bank_mask:0xf bound_ctrl:1
	v_add_f32_dpp v25, v25, v25 row_ror:4 row_mask:0xf bank_mask:0xf bound_ctrl:1
	v_pk_fma_f32 v[26:27], v[168:169], v[198:199], v[26:27] op_sel_hi:[1,0,1]
	v_add_f32_dpp v164, v24, v24 row_ror:4 row_mask:0xf bank_mask:0xf bound_ctrl:1
	v_add_f32_dpp v24, v25, v25 row_ror:8 row_mask:0xf bank_mask:0xf bound_ctrl:1
	v_pk_fma_f32 v[196:197], v[176:177], v[24:25], v[26:27] op_sel_hi:[1,0,1]
	v_add_f32_dpp v210, v164, v164 row_ror:8 row_mask:0xf bank_mask:0x4 bound_ctrl:1
	v_pk_fma_f32 v[34:35], v[178:179], v[24:25], v[34:35] op_sel_hi:[1,0,1]
	ds_read_b128 v[24:27], v28 offset:21504
	ds_read_b128 v[164:167], v28 offset:21760
	ds_read_b128 v[168:171], v28 offset:22016
	ds_read_b128 v[172:175], v28 offset:22528
	ds_read_b128 v[176:179], v28 offset:22784
	ds_read_b32 v198, v29 offset:22272
	s_waitcnt lgkmcnt(8)
	v_pk_mul_f32 v[190:191], v[190:191], v[34:35]
	v_pk_mul_f32 v[32:33], v[32:33], v[34:35]
	v_pk_fma_f32 v[188:189], v[188:189], v[196:197], v[190:191]
	v_pk_fma_f32 v[30:31], v[30:31], v[196:197], v[32:33]
	v_add_f32_e32 v206, v188, v189
	v_pk_mul_f32 v[32:33], v[180:181], v[196:197]
	v_add_f32_e32 v30, v30, v31
	v_add_f32_dpp v31, v206, v206 quad_perm:[1,0,3,2] row_mask:0xf bank_mask:0xf bound_ctrl:1
	v_pk_mul_f32 v[34:35], v[182:183], v[34:35]
	v_add_f32_dpp v30, v30, v30 quad_perm:[1,0,3,2] row_mask:0xf bank_mask:0xf bound_ctrl:1
	s_waitcnt lgkmcnt(6)
	v_add_f32_dpp v31, v31, v31 quad_perm:[2,3,0,1] row_mask:0xf bank_mask:0xf bound_ctrl:1
	v_pk_fma_f32 v[34:35], v[186:187], v[200:201], v[34:35] op_sel_hi:[1,0,1]
	v_add_f32_dpp v30, v30, v30 quad_perm:[2,3,0,1] row_mask:0xf bank_mask:0xf bound_ctrl:1
	v_add_f32_dpp v31, v31, v31 row_ror:4 row_mask:0xf bank_mask:0xf bound_ctrl:1
	v_pk_fma_f32 v[32:33], v[184:185], v[200:201], v[32:33] op_sel_hi:[1,0,1]
	v_add_f32_dpp v180, v30, v30 row_ror:4 row_mask:0xf bank_mask:0xf bound_ctrl:1
	v_add_f32_dpp v30, v31, v31 row_ror:8 row_mask:0xf bank_mask:0xf bound_ctrl:1
	v_pk_fma_f32 v[196:197], v[192:193], v[30:31], v[32:33] op_sel_hi:[1,0,1]
	v_add_f32_dpp v207, v180, v180 row_ror:8 row_mask:0xf bank_mask:0x8 bound_ctrl:1
	v_pk_fma_f32 v[34:35], v[194:195], v[30:31], v[34:35] op_sel_hi:[1,0,1]
	ds_read_b128 v[30:33], v28 offset:23040
	ds_read_b128 v[180:183], v28 offset:23296
	ds_read_b128 v[184:187], v28 offset:23552
	ds_read_b128 v[188:191], v28 offset:24064
	ds_read_b128 v[192:195], v28 offset:24320
	ds_read_b32 v200, v29 offset:23808
	s_waitcnt lgkmcnt(8)
; #define LAS __attribute__((address_space(3)))
; __device__ __forceinline__ void rwkv_scan_prompt(const Params& p, LAS unsigned char* lds, int bh, int rq) {
;     ...
;             for (int tk = 0; tk < TC; ++tk) {
;                 f32x4 nr4 = r4, nd4 = d4, nk4 = k4, na4 = a4, nb4 = b4; float nvv = vv;
;                 if (tk < TC - 1) {
;                     const LAS float* o = ob + (tk + 1) * 6 * 64;
;                     nr4 = *(const LAS f32x4*)(o + cg_ * 4); nd4 = *(const LAS f32x4*)(o + 64 + cg_ * 4); nk4 = *(const LAS f32x4*)(o + 128 + cg_ * 4);
;                     na4 = *(const LAS f32x4*)(o + 256 + cg_ * 4); nb4 = *(const LAS f32x4*)(o + 320 + cg_ * 4);
;                     nvv = o[192 + rq * 16 + rloc];
;                 }
;                 __builtin_amdgcn_sched_barrier(0);
;                 typedef float f32x2_ __attribute__((ext_vector_type(2)));
;                 f32x2_ ta = (f32x2_){S[0], S[1]} * (f32x2_){a4[0], a4[1]}; ta = (f32x2_){S[2], S[3]} * (f32x2_){a4[2], a4[3]} + ta;
;                 f32x2_ ty = (f32x2_){S[0], S[1]} * (f32x2_){rp[0], rp[1]}; ty = (f32x2_){S[2], S[3]} * (f32x2_){rp[2], rp[3]} + ty;
;                 const f32x4 T = S * d4 + vv * k4;
;                 float sa = ta[0] + ta[1];
;                 float yp = ty[0] + ty[1];
;                 sa = dpp_add<0xB1>(sa); yp = dpp_add<0xB1>(yp);
;                 sa = dpp_add<0x4E>(sa); yp = dpp_add<0x4E>(yp);
;                 sa = dpp_add<0x124>(sa); yp = dpp_add<0x124>(yp);
;                 sa = dpp_add<0x128>(sa); yp = dpp_add<0x128>(yp);
;                 if (tk > 0) yk[(tk - 1) >> 4] = (cg_ == ((tk - 1) & 15)) ? yp : yk[(tk - 1) >> 4];
;                 S = sa * b4 + T;
;                 rp = r4;
;                 r4 = nr4; d4 = nd4; k4 = nk4; a4 = na4; b4 = nb4; vv = nvv;
	v_pk_mul_f32 v[174:175], v[174:175], v[34:35]
	v_pk_mul_f32 v[162:163], v[162:163], v[34:35]
	v_pk_fma_f32 v[172:173], v[172:173], v[196:197], v[174:175]
	v_pk_fma_f32 v[160:161], v[160:161], v[196:197], v[162:163]
	v_add_f32_e32 v206, v172, v173
	v_pk_mul_f32 v[162:163], v[164:165], v[196:197]
	v_add_f32_e32 v160, v160, v161
	v_add_f32_dpp v161, v206, v206 quad_perm:[1,0,3,2] row_mask:0xf bank_mask:0xf bound_ctrl:1
	v_pk_mul_f32 v[34:35], v[166:167], v[34:35]
	v_add_f32_dpp v160, v160, v160 quad_perm:[1,0,3,2] row_mask:0xf bank_mask:0xf bound_ctrl:1
	s_waitcnt lgkmcnt(6)
	v_add_f32_dpp v161, v161, v161 quad_perm:[2,3,0,1] row_mask:0xf bank_mask:0xf bound_ctrl:1
	v_pk_fma_f32 v[34:35], v[170:171], v[198:199], v[34:35] op_sel_hi:[1,0,1]
	v_add_f32_dpp v160, v160, v160 quad_perm:[2,3,0,1] row_mask:0xf bank_mask:0xf bound_ctrl:1
	v_add_f32_dpp v161, v161, v161 row_ror:4 row_mask:0xf bank_mask:0xf bound_ctrl:1
	v_pk_fma_f32 v[162:163], v[168:169], v[198:199], v[162:163] op_sel_hi:[1,0,1]
	v_add_f32_dpp v164, v160, v160 row_ror:4 row_mask:0xf bank_mask:0xf bound_ctrl:1
	v_add_f32_dpp v160, v161, v161 row_ror:8 row_mask:0xf bank_mask:0xf bound_ctrl:1
	v_pk_fma_f32 v[196:197], v[176:177], v[160:161], v[162:163] op_sel_hi:[1,0,1]
	v_add_f32_dpp v208, v164, v164 row_ror:8 row_mask:0xf bank_mask:0x8 bound_ctrl:1
	v_pk_fma_f32 v[34:35], v[178:179], v[160:161], v[34:35] op_sel_hi:[1,0,1]
	ds_read_b128 v[160:163], v28 offset:24576
	ds_read_b128 v[164:167], v28 offset:24832
	ds_read_b128 v[168:171], v28 offset:25088
	ds_read_b128 v[172:175], v28 offset:25600
	ds_read_b128 v[176:179], v28 offset:25856
	ds_read_b32 v198, v29 offset:25344
	s_waitcnt lgkmcnt(8)
	v_pk_mul_f32 v[190:191], v[190:191], v[34:35]
	v_pk_mul_f32 v[26:27], v[26:27], v[34:35]
	v_pk_fma_f32 v[188:189], v[188:189], v[196:197], v[190:191]
	v_pk_fma_f32 v[24:25], v[24:25], v[196:197], v[26:27]
	v_add_f32_e32 v206, v188, v189
	v_pk_mul_f32 v[26:27], v[180:181], v[196:197]
	v_add_f32_e32 v24, v24, v25
	v_add_f32_dpp v25, v206, v206 quad_perm:[1,0,3,2] row_mask:0xf bank_mask:0xf bound_ctrl:1
	v_pk_mul_f32 v[34:35], v[182:183], v[34:35]
	v_add_f32_dpp v24, v24, v24 quad_perm:[1,0,3,2] row_mask:0xf bank_mask:0xf bound_ctrl:1
	s_waitcnt lgkmcnt(6)
	v_add_f32_dpp v25, v25, v25 quad_perm:[2,3,0,1] row_mask:0xf bank_mask:0xf bound_ctrl:1
	v_pk_fma_f32 v[34:35], v[186:187], v[200:201], v[34:35] op_sel_hi:[1,0,1]
	v_add_f32_dpp v24, v24, v24 quad_perm:[2,3,0,1] row_mask:0xf bank_mask:0xf bound_ctrl:1
	v_add_f32_dpp v25, v25, v25 row_ror:4 row_mask:0xf bank_mask:0xf bound_ctrl:1
	v_pk_fma_f32 v[26:27], v[184:185], v[200:201], v[26:27] op_sel_hi:[1,0,1]
	v_add_f32_dpp v180, v24, v24 row_ror:4 row_mask:0xf bank_mask:0xf bound_ctrl:1
	v_add_f32_dpp v24, v25, v25 row_ror:8 row_mask:0xf bank_mask:0xf bound_ctrl:1
	v_pk_fma_f32 v[196:197], v[192:193], v[24:25], v[26:27] op_sel_hi:[1,0,1]
	v_add_f32_dpp v209, v180, v180 row_ror:8 row_mask:0xf bank_mask:0x8 bound_ctrl:1
	v_pk_fma_f32 v[34:35], v[194:195], v[24:25], v[34:35] op_sel_hi:[1,0,1]
	ds_read_b128 v[24:27], v28 offset:26112
	ds_read_b128 v[180:183], v28 offset:26368
	ds_read_b128 v[184:187], v28 offset:26624
	ds_read_b128 v[188:191], v28 offset:27136
	ds_read_b128 v[192:195], v28 offset:27392
	ds_read_b32 v200, v29 offset:26880
	s_waitcnt lgkmcnt(8)
	v_pk_mul_f32 v[174:175], v[174:175], v[34:35]
	v_pk_mul_f32 v[32:33], v[32:33], v[34:35]
	v_pk_fma_f32 v[172:173], v[172:173], v[196:197], v[174:175]
	v_pk_fma_f32 v[30:31], v[30:31], v[196:197], v[32:33]
	v_add_f32_e32 v206, v172, v173
	v_pk_mul_f32 v[32:33], v[164:165], v[196:197]
	v_add_f32_e32 v30, v30, v31
	v_add_f32_dpp v31, v206, v206 quad_perm:[1,0,3,2] row_mask:0xf bank_mask:0xf bound_ctrl:1
	v_pk_mul_f32 v[34:35], v[166:167], v[34:35]
	v_add_f32_dpp v30, v30, v30 quad_perm:[1,0,3,2] row_mask:0xf bank_mask:0xf bound_ctrl:1
	s_waitcnt lgkmcnt(6)
	v_add_f32_dpp v31, v31, v31 quad_perm:[2,3,0,1] row_mask:0xf bank_mask:0xf bound_ctrl:1
	v_pk_fma_f32 v[34:35], v[170:171], v[198:199], v[34:35] op_sel_hi:[1,0,1]
	v_add_f32_dpp v30, v30, v30 quad_perm:[2,3,0,1] row_mask:0xf bank_mask:0xf bound_ctrl:1
	v_add_f32_dpp v31, v31, v31 row_ror:4 row_mask:0xf bank_mask:0xf bound_ctrl:1
	v_pk_fma_f32 v[32:33], v[168:169], v[198:199], v[32:33] op_sel_hi:[1,0,1]
	v_add_f32_dpp v30, v30, v30 row_ror:4 row_mask:0xf bank_mask:0xf bound_ctrl:1
	v_add_f32_dpp v164, v31, v31 row_ror:8 row_mask:0xf bank_mask:0xf bound_ctrl:1
	v_pk_fma_f32 v[196:197], v[176:177], v[164:165], v[32:33] op_sel_hi:[1,0,1]
	v_add_f32_dpp v210, v30, v30 row_ror:8 row_mask:0xf bank_mask:0x8 bound_ctrl:1
	v_cndmask_b32_e64 v30, v207, v208, s[96:97]
	v_cndmask_b32_e64 v30, v30, v209, s[98:99]
	v_cndmask_b32_e64 v30, v30, v210, s[100:101]
	v_pk_fma_f32 v[198:199], v[178:179], v[164:165], v[34:35] op_sel_hi:[1,0,1]
	ds_read_b128 v[32:35], v28 offset:27648
	ds_read_b128 v[164:167], v28 offset:27904
	ds_read_b128 v[168:171], v28 offset:28160
	ds_read_b128 v[172:175], v28 offset:28672
	ds_read_b128 v[176:179], v28 offset:28928
	ds_read_b32 v202, v29 offset:28416
	s_waitcnt lgkmcnt(8)
	v_pk_mul_f32 v[190:191], v[190:191], v[198:199]
	v_pk_mul_f32 v[162:163], v[162:163], v[198:199]
	v_pk_fma_f32 v[188:189], v[188:189], v[196:197], v[190:191]
	v_pk_fma_f32 v[160:161], v[160:161], v[196:197], v[162:163]
	v_add_f32_e32 v31, v188, v189
	v_add_f32_e32 v160, v160, v161
	v_pk_mul_f32 v[162:163], v[180:181], v[196:197]
	v_add_f32_dpp v31, v31, v31 quad_perm:[1,0,3,2] row_mask:0xf bank_mask:0xf bound_ctrl:1
	v_add_f32_dpp v160, v160, v160 quad_perm:[1,0,3,2] row_mask:0xf bank_mask:0xf bound_ctrl:1
	v_pk_mul_f32 v[180:181], v[182:183], v[198:199]
	v_add_f32_dpp v31, v31, v31 quad_perm:[2,3,0,1] row_mask:0xf bank_mask:0xf bound_ctrl:1
	v_add_f32_dpp v160, v160, v160 quad_perm:[2,3,0,1] row_mask:0xf bank_mask:0xf bound_ctrl:1
	s_waitcnt lgkmcnt(6)
; #define LAS __attribute__((address_space(3)))
; __device__ __forceinline__ void rwkv_scan_prompt(const Params& p, LAS unsigned char* lds, int bh, int rq) {
;     ...
;             for (int tk = 0; tk < TC; ++tk) {
;                 f32x4 nr4 = r4, nd4 = d4, nk4 = k4, na4 = a4, nb4 = b4; float nvv = vv;
;                 if (tk < TC - 1) {
;                     const LAS float* o = ob + (tk + 1) * 6 * 64;
;                     nr4 = *(const LAS f32x4*)(o + cg_ * 4); nd4 = *(const LAS f32x4*)(o + 64 + cg_ * 4); nk4 = *(const LAS f32x4*)(o + 128 + cg_ * 4);
;                     na4 = *(const LAS f32x4*)(o + 256 + cg_ * 4); nb4 = *(const LAS f32x4*)(o + 320 + cg_ * 4);
;                     nvv = o[192 + rq * 16 + rloc];
;                 }
;                 __builtin_amdgcn_sched_barrier(0);
;                 typedef float f32x2_ __attribute__((ext_vector_type(2)));
;                 f32x2_ ta = (f32x2_){S[0], S[1]} * (f32x2_){a4[0], a4[1]}; ta = (f32x2_){S[2], S[3]} * (f32x2_){a4[2], a4[3]} + ta;
;                 f32x2_ ty = (f32x2_){S[0], S[1]} * (f32x2_){rp[0], rp[1]}; ty = (f32x2_){S[2], S[3]} * (f32x2_){rp[2], rp[3]} + ty;
;                 const f32x4 T = S * d4 + vv * k4;
;                 float sa = ta[0] + ta[1];
;                 float yp = ty[0] + ty[1];
;                 sa = dpp_add<0xB1>(sa); yp = dpp_add<0xB1>(yp);
;                 sa = dpp_add<0x4E>(sa); yp = dpp_add<0x4E>(yp);
;                 sa = dpp_add<0x124>(sa); yp = dpp_add<0x124>(yp);
;                 sa = dpp_add<0x128>(sa); yp = dpp_add<0x128>(yp);
;                 if (tk > 0) yk[(tk - 1) >> 4] = (cg_ == ((tk - 1) & 15)) ? yp : yk[(tk - 1) >> 4];
;                 S = sa * b4 + T;
;                 rp = r4;
;                 r4 = nr4; d4 = nd4; k4 = nk4; a4 = na4; b4 = nb4; vv = nvv;
	v_pk_fma_f32 v[180:181], v[186:187], v[200:201], v[180:181] op_sel_hi:[1,0,1]
	v_add_f32_dpp v31, v31, v31 row_ror:4 row_mask:0xf bank_mask:0xf bound_ctrl:1
	v_pk_fma_f32 v[162:163], v[184:185], v[200:201], v[162:163] op_sel_hi:[1,0,1]
	v_add_f32_dpp v161, v160, v160 row_ror:4 row_mask:0xf bank_mask:0xf bound_ctrl:1
	v_add_f32_dpp v160, v31, v31 row_ror:8 row_mask:0xf bank_mask:0xf bound_ctrl:1
	v_pk_fma_f32 v[196:197], v[192:193], v[160:161], v[162:163] op_sel_hi:[1,0,1]
	v_add_f32_dpp v207, v161, v161 row_ror:8 row_mask:0xf bank_mask:0x1 bound_ctrl:1
	v_pk_fma_f32 v[198:199], v[194:195], v[160:161], v[180:181] op_sel_hi:[1,0,1]
	ds_read_b128 v[160:163], v28 offset:29184
	ds_read_b128 v[180:183], v28 offset:29440
	ds_read_b128 v[184:187], v28 offset:29696
	ds_read_b128 v[188:191], v28 offset:30208
	ds_read_b128 v[192:195], v28 offset:30464
	ds_read_b32 v200, v29 offset:29952
	s_waitcnt lgkmcnt(8)
	v_pk_mul_f32 v[174:175], v[174:175], v[198:199]
	v_pk_mul_f32 v[26:27], v[26:27], v[198:199]
	v_pk_fma_f32 v[172:173], v[172:173], v[196:197], v[174:175]
	v_pk_fma_f32 v[24:25], v[24:25], v[196:197], v[26:27]
	v_add_f32_e32 v206, v172, v173
	v_pk_mul_f32 v[26:27], v[164:165], v[196:197]
	v_add_f32_e32 v24, v24, v25
	s_waitcnt lgkmcnt(6)
	v_add_f32_dpp v25, v206, v206 quad_perm:[1,0,3,2] row_mask:0xf bank_mask:0xf bound_ctrl:1
	v_pk_mul_f32 v[164:165], v[166:167], v[198:199]
	v_add_f32_dpp v24, v24, v24 quad_perm:[1,0,3,2] row_mask:0xf bank_mask:0xf bound_ctrl:1
	v_add_f32_dpp v25, v25, v25 quad_perm:[2,3,0,1] row_mask:0xf bank_mask:0xf bound_ctrl:1
	v_pk_fma_f32 v[164:165], v[170:171], v[202:203], v[164:165] op_sel_hi:[1,0,1]
	v_add_f32_dpp v24, v24, v24 quad_perm:[2,3,0,1] row_mask:0xf bank_mask:0xf bound_ctrl:1
	v_add_f32_dpp v25, v25, v25 row_ror:4 row_mask:0xf bank_mask:0xf bound_ctrl:1
	v_pk_fma_f32 v[26:27], v[168:169], v[202:203], v[26:27] op_sel_hi:[1,0,1]
	v_add_f32_dpp v166, v24, v24 row_ror:4 row_mask:0xf bank_mask:0xf bound_ctrl:1
	v_add_f32_dpp v24, v25, v25 row_ror:8 row_mask:0xf bank_mask:0xf bound_ctrl:1
	v_pk_fma_f32 v[196:197], v[176:177], v[24:25], v[26:27] op_sel_hi:[1,0,1]
	v_add_f32_dpp v208, v166, v166 row_ror:8 row_mask:0xf bank_mask:0x1 bound_ctrl:1
	v_pk_fma_f32 v[198:199], v[178:179], v[24:25], v[164:165] op_sel_hi:[1,0,1]
	ds_read_b128 v[24:27], v28 offset:30720
	ds_read_b128 v[164:167], v28 offset:30976
	ds_read_b128 v[168:171], v28 offset:31232
	ds_read_b128 v[172:175], v28 offset:31744
	ds_read_b128 v[176:179], v28 offset:32000
	ds_read_b32 v202, v29 offset:31488
	s_waitcnt lgkmcnt(8)
	v_pk_mul_f32 v[190:191], v[190:191], v[198:199]
	v_pk_mul_f32 v[34:35], v[34:35], v[198:199]
	v_pk_fma_f32 v[188:189], v[188:189], v[196:197], v[190:191]
	v_pk_fma_f32 v[32:33], v[32:33], v[196:197], v[34:35]
	v_add_f32_e32 v206, v188, v189
	v_pk_mul_f32 v[34:35], v[180:181], v[196:197]
	v_add_f32_e32 v32, v32, v33
	s_waitcnt lgkmcnt(6)
	v_add_f32_dpp v33, v206, v206 quad_perm:[1,0,3,2] row_mask:0xf bank_mask:0xf bound_ctrl:1
	v_pk_mul_f32 v[180:181], v[182:183], v[198:199]
	v_add_f32_dpp v32, v32, v32 quad_perm:[1,0,3,2] row_mask:0xf bank_mask:0xf bound_ctrl:1
	v_add_f32_dpp v33, v33, v33 quad_perm:[2,3,0,1] row_mask:0xf bank_mask:0xf bound_ctrl:1
	v_pk_fma_f32 v[180:181], v[186:187], v[200:201], v[180:181] op_sel_hi:[1,0,1]
	v_add_f32_dpp v32, v32, v32 quad_perm:[2,3,0,1] row_mask:0xf bank_mask:0xf bound_ctrl:1
	v_add_f32_dpp v33, v33, v33 row_ror:4 row_mask:0xf bank_mask:0xf bound_ctrl:1
	v_pk_fma_f32 v[34:35], v[184:185], v[200:201], v[34:35] op_sel_hi:[1,0,1]
	v_add_f32_dpp v182, v32, v32 row_ror:4 row_mask:0xf bank_mask:0xf bound_ctrl:1
	v_add_f32_dpp v32, v33, v33 row_ror:8 row_mask:0xf bank_mask:0xf bound_ctrl:1
	v_pk_fma_f32 v[196:197], v[192:193], v[32:33], v[34:35] op_sel_hi:[1,0,1]
	v_add_f32_dpp v209, v182, v182 row_ror:8 row_mask:0xf bank_mask:0x1 bound_ctrl:1
	v_pk_fma_f32 v[198:199], v[194:195], v[32:33], v[180:181] op_sel_hi:[1,0,1]
	ds_read_b128 v[32:35], v28 offset:32256
	ds_read_b128 v[180:183], v28 offset:32512
	ds_read_b128 v[184:187], v28 offset:32768
	ds_read_b128 v[188:191], v28 offset:33280
	ds_read_b128 v[192:195], v28 offset:33536
	ds_read_b32 v200, v29 offset:33024
	s_waitcnt lgkmcnt(8)
	v_pk_mul_f32 v[174:175], v[174:175], v[198:199]
	v_pk_mul_f32 v[162:163], v[162:163], v[198:199]
	v_pk_fma_f32 v[172:173], v[172:173], v[196:197], v[174:175]
	v_pk_fma_f32 v[160:161], v[160:161], v[196:197], v[162:163]
	v_add_f32_e32 v206, v172, v173
	v_pk_mul_f32 v[162:163], v[164:165], v[196:197]
	v_add_f32_e32 v160, v160, v161
	s_waitcnt lgkmcnt(6)
	v_add_f32_dpp v161, v206, v206 quad_perm:[1,0,3,2] row_mask:0xf bank_mask:0xf bound_ctrl:1
	v_pk_mul_f32 v[164:165], v[166:167], v[198:199]
	v_add_f32_dpp v160, v160, v160 quad_perm:[1,0,3,2] row_mask:0xf bank_mask:0xf bound_ctrl:1
	v_add_f32_dpp v161, v161, v161 quad_perm:[2,3,0,1] row_mask:0xf bank_mask:0xf bound_ctrl:1
	v_pk_fma_f32 v[164:165], v[170:171], v[202:203], v[164:165] op_sel_hi:[1,0,1]
	v_add_f32_dpp v160, v160, v160 quad_perm:[2,3,0,1] row_mask:0xf bank_mask:0xf bound_ctrl:1
	v_add_f32_dpp v161, v161, v161 row_ror:4 row_mask:0xf bank_mask:0xf bound_ctrl:1
	v_pk_fma_f32 v[162:163], v[168:169], v[202:203], v[162:163] op_sel_hi:[1,0,1]
	v_add_f32_dpp v166, v160, v160 row_ror:4 row_mask:0xf bank_mask:0xf bound_ctrl:1
	v_add_f32_dpp v160, v161, v161 row_ror:8 row_mask:0xf bank_mask:0xf bound_ctrl:1
	v_pk_fma_f32 v[196:197], v[176:177], v[160:161], v[162:163] op_sel_hi:[1,0,1]
	v_add_f32_dpp v210, v166, v166 row_ror:8 row_mask:0xf bank_mask:0x1 bound_ctrl:1
	v_pk_fma_f32 v[198:199], v[178:179], v[160:161], v[164:165] op_sel_hi:[1,0,1]
	ds_read_b128 v[160:163], v28 offset:33792
	ds_read_b128 v[164:167], v28 offset:34048
	ds_read_b128 v[168:171], v28 offset:34304
	ds_read_b128 v[172:175], v28 offset:34816
	ds_read_b128 v[176:179], v28 offset:35072
	ds_read_b32 v202, v29 offset:34560
	s_waitcnt lgkmcnt(8)
; #define LAS __attribute__((address_space(3)))
; __device__ __forceinline__ void rwkv_scan_prompt(const Params& p, LAS unsigned char* lds, int bh, int rq) {
;     ...
;             for (int tk = 0; tk < TC; ++tk) {
;                 f32x4 nr4 = r4, nd4 = d4, nk4 = k4, na4 = a4, nb4 = b4; float nvv = vv;
;                 if (tk < TC - 1) {
;                     const LAS float* o = ob + (tk + 1) * 6 * 64;
;                     nr4 = *(const LAS f32x4*)(o + cg_ * 4); nd4 = *(const LAS f32x4*)(o + 64 + cg_ * 4); nk4 = *(const LAS f32x4*)(o + 128 + cg_ * 4);
;                     na4 = *(const LAS f32x4*)(o + 256 + cg_ * 4); nb4 = *(const LAS f32x4*)(o + 320 + cg_ * 4);
;                     nvv = o[192 + rq * 16 + rloc];
;                 }
;                 __builtin_amdgcn_sched_barrier(0);
;                 typedef float f32x2_ __attribute__((ext_vector_type(2)));
;                 f32x2_ ta = (f32x2_){S[0], S[1]} * (f32x2_){a4[0], a4[1]}; ta = (f32x2_){S[2], S[3]} * (f32x2_){a4[2], a4[3]} + ta;
;                 f32x2_ ty = (f32x2_){S[0], S[1]} * (f32x2_){rp[0], rp[1]}; ty = (f32x2_){S[2], S[3]} * (f32x2_){rp[2], rp[3]} + ty;
;                 const f32x4 T = S * d4 + vv * k4;
;                 float sa = ta[0] + ta[1];
;                 float yp = ty[0] + ty[1];
;                 sa = dpp_add<0xB1>(sa); yp = dpp_add<0xB1>(yp);
;                 sa = dpp_add<0x4E>(sa); yp = dpp_add<0x4E>(yp);
;                 sa = dpp_add<0x124>(sa); yp = dpp_add<0x124>(yp);
;                 sa = dpp_add<0x128>(sa); yp = dpp_add<0x128>(yp);
;                 if (tk > 0) yk[(tk - 1) >> 4] = (cg_ == ((tk - 1) & 15)) ? yp : yk[(tk - 1) >> 4];
;                 S = sa * b4 + T;
;                 rp = r4;
;                 r4 = nr4; d4 = nd4; k4 = nk4; a4 = na4; b4 = nb4; vv = nvv;
	v_pk_mul_f32 v[190:191], v[190:191], v[198:199]
	v_pk_mul_f32 v[26:27], v[26:27], v[198:199]
	v_pk_fma_f32 v[188:189], v[188:189], v[196:197], v[190:191]
	v_pk_fma_f32 v[24:25], v[24:25], v[196:197], v[26:27]
	v_add_f32_e32 v206, v188, v189
	v_pk_mul_f32 v[26:27], v[180:181], v[196:197]
	v_add_f32_e32 v24, v24, v25
	s_waitcnt lgkmcnt(6)
	v_add_f32_dpp v25, v206, v206 quad_perm:[1,0,3,2] row_mask:0xf bank_mask:0xf bound_ctrl:1
	v_pk_mul_f32 v[180:181], v[182:183], v[198:199]
	v_add_f32_dpp v24, v24, v24 quad_perm:[1,0,3,2] row_mask:0xf bank_mask:0xf bound_ctrl:1
	v_add_f32_dpp v25, v25, v25 quad_perm:[2,3,0,1] row_mask:0xf bank_mask:0xf bound_ctrl:1
	v_pk_fma_f32 v[180:181], v[186:187], v[200:201], v[180:181] op_sel_hi:[1,0,1]
	v_add_f32_dpp v24, v24, v24 quad_perm:[2,3,0,1] row_mask:0xf bank_mask:0xf bound_ctrl:1
	v_add_f32_dpp v25, v25, v25 row_ror:4 row_mask:0xf bank_mask:0xf bound_ctrl:1
	v_pk_fma_f32 v[26:27], v[184:185], v[200:201], v[26:27] op_sel_hi:[1,0,1]
	v_add_f32_dpp v182, v24, v24 row_ror:4 row_mask:0xf bank_mask:0xf bound_ctrl:1
	v_add_f32_dpp v24, v25, v25 row_ror:8 row_mask:0xf bank_mask:0xf bound_ctrl:1
	v_pk_fma_f32 v[196:197], v[192:193], v[24:25], v[26:27] op_sel_hi:[1,0,1]
	v_add_f32_dpp v207, v182, v182 row_ror:8 row_mask:0xf bank_mask:0x2 bound_ctrl:1
	v_pk_fma_f32 v[198:199], v[194:195], v[24:25], v[180:181] op_sel_hi:[1,0,1]
	ds_read_b128 v[24:27], v28 offset:35328
	ds_read_b128 v[180:183], v28 offset:35584
	ds_read_b128 v[184:187], v28 offset:35840
	ds_read_b128 v[188:191], v28 offset:36352
	ds_read_b128 v[192:195], v28 offset:36608
	ds_read_b32 v200, v29 offset:36096
	s_waitcnt lgkmcnt(8)
	v_pk_mul_f32 v[174:175], v[174:175], v[198:199]
	v_pk_mul_f32 v[34:35], v[34:35], v[198:199]
	v_pk_fma_f32 v[172:173], v[172:173], v[196:197], v[174:175]
	v_pk_fma_f32 v[32:33], v[32:33], v[196:197], v[34:35]
	v_add_f32_e32 v206, v172, v173
	v_pk_mul_f32 v[34:35], v[164:165], v[196:197]
	v_add_f32_e32 v32, v32, v33
	s_waitcnt lgkmcnt(6)
	v_add_f32_dpp v33, v206, v206 quad_perm:[1,0,3,2] row_mask:0xf bank_mask:0xf bound_ctrl:1
	v_pk_mul_f32 v[164:165], v[166:167], v[198:199]
	v_add_f32_dpp v32, v32, v32 quad_perm:[1,0,3,2] row_mask:0xf bank_mask:0xf bound_ctrl:1
	v_add_f32_dpp v33, v33, v33 quad_perm:[2,3,0,1] row_mask:0xf bank_mask:0xf bound_ctrl:1
	v_pk_fma_f32 v[164:165], v[170:171], v[202:203], v[164:165] op_sel_hi:[1,0,1]
	v_add_f32_dpp v32, v32, v32 quad_perm:[2,3,0,1] row_mask:0xf bank_mask:0xf bound_ctrl:1
	v_add_f32_dpp v33, v33, v33 row_ror:4 row_mask:0xf bank_mask:0xf bound_ctrl:1
	v_pk_fma_f32 v[34:35], v[168:169], v[202:203], v[34:35] op_sel_hi:[1,0,1]
	v_add_f32_dpp v166, v32, v32 row_ror:4 row_mask:0xf bank_mask:0xf bound_ctrl:1
	v_add_f32_dpp v32, v33, v33 row_ror:8 row_mask:0xf bank_mask:0xf bound_ctrl:1
	v_pk_fma_f32 v[196:197], v[176:177], v[32:33], v[34:35] op_sel_hi:[1,0,1]
	v_add_f32_dpp v208, v166, v166 row_ror:8 row_mask:0xf bank_mask:0x2 bound_ctrl:1
	v_pk_fma_f32 v[198:199], v[178:179], v[32:33], v[164:165] op_sel_hi:[1,0,1]
	ds_read_b128 v[32:35], v28 offset:36864
	ds_read_b128 v[164:167], v28 offset:37120
	ds_read_b128 v[168:171], v28 offset:37376
	ds_read_b128 v[172:175], v28 offset:37888
	ds_read_b128 v[176:179], v28 offset:38144
	ds_read_b32 v202, v29 offset:37632
	s_waitcnt lgkmcnt(8)
	v_pk_mul_f32 v[190:191], v[190:191], v[198:199]
	v_pk_mul_f32 v[162:163], v[162:163], v[198:199]
	v_pk_fma_f32 v[188:189], v[188:189], v[196:197], v[190:191]
	v_pk_fma_f32 v[160:161], v[160:161], v[196:197], v[162:163]
	v_add_f32_e32 v206, v188, v189
	v_pk_mul_f32 v[162:163], v[180:181], v[196:197]
	v_add_f32_e32 v160, v160, v161
	s_waitcnt lgkmcnt(6)
	v_add_f32_dpp v161, v206, v206 quad_perm:[1,0,3,2] row_mask:0xf bank_mask:0xf bound_ctrl:1
	v_pk_mul_f32 v[180:181], v[182:183], v[198:199]
	v_add_f32_dpp v160, v160, v160 quad_perm:[1,0,3,2] row_mask:0xf bank_mask:0xf bound_ctrl:1
	v_add_f32_dpp v161, v161, v161 quad_perm:[2,3,0,1] row_mask:0xf bank_mask:0xf bound_ctrl:1
	v_pk_fma_f32 v[180:181], v[186:187], v[200:201], v[180:181] op_sel_hi:[1,0,1]
	v_add_f32_dpp v160, v160, v160 quad_perm:[2,3,0,1] row_mask:0xf bank_mask:0xf bound_ctrl:1
	v_add_f32_dpp v161, v161, v161 row_ror:4 row_mask:0xf bank_mask:0xf bound_ctrl:1
	v_pk_fma_f32 v[162:163], v[184:185], v[200:201], v[162:163] op_sel_hi:[1,0,1]
	v_add_f32_dpp v182, v160, v160 row_ror:4 row_mask:0xf bank_mask:0xf bound_ctrl:1
	v_add_f32_dpp v160, v161, v161 row_ror:8 row_mask:0xf bank_mask:0xf bound_ctrl:1
	v_pk_fma_f32 v[196:197], v[192:193], v[160:161], v[162:163] op_sel_hi:[1,0,1]
	v_add_f32_dpp v209, v182, v182 row_ror:8 row_mask:0xf bank_mask:0x2 bound_ctrl:1
	v_pk_fma_f32 v[198:199], v[194:195], v[160:161], v[180:181] op_sel_hi:[1,0,1]
	ds_read_b128 v[160:163], v28 offset:38400
	ds_read_b128 v[180:183], v28 offset:38656
	ds_read_b128 v[184:187], v28 offset:38912
	ds_read_b128 v[188:191], v28 offset:39424
	ds_read_b128 v[192:195], v28 offset:39680
	ds_read_b32 v200, v29 offset:39168
	s_waitcnt lgkmcnt(8)
	v_pk_mul_f32 v[174:175], v[174:175], v[198:199]
	v_pk_mul_f32 v[26:27], v[26:27], v[198:199]
	v_pk_fma_f32 v[172:173], v[172:173], v[196:197], v[174:175]
	v_pk_fma_f32 v[24:25], v[24:25], v[196:197], v[26:27]
	v_add_f32_e32 v206, v172, v173
	v_pk_mul_f32 v[26:27], v[164:165], v[196:197]
	v_add_f32_e32 v24, v24, v25
	s_waitcnt lgkmcnt(6)
; #define LAS __attribute__((address_space(3)))
; __device__ __forceinline__ void rwkv_scan_prompt(const Params& p, LAS unsigned char* lds, int bh, int rq) {
;     ...
;             for (int tk = 0; tk < TC; ++tk) {
;                 f32x4 nr4 = r4, nd4 = d4, nk4 = k4, na4 = a4, nb4 = b4; float nvv = vv;
;                 if (tk < TC - 1) {
;                     const LAS float* o = ob + (tk + 1) * 6 * 64;
;                     nr4 = *(const LAS f32x4*)(o + cg_ * 4); nd4 = *(const LAS f32x4*)(o + 64 + cg_ * 4); nk4 = *(const LAS f32x4*)(o + 128 + cg_ * 4);
;                     na4 = *(const LAS f32x4*)(o + 256 + cg_ * 4); nb4 = *(const LAS f32x4*)(o + 320 + cg_ * 4);
;                     nvv = o[192 + rq * 16 + rloc];
;                 }
;                 __builtin_amdgcn_sched_barrier(0);
;                 typedef float f32x2_ __attribute__((ext_vector_type(2)));
;                 f32x2_ ta = (f32x2_){S[0], S[1]} * (f32x2_){a4[0], a4[1]}; ta = (f32x2_){S[2], S[3]} * (f32x2_){a4[2], a4[3]} + ta;
;                 f32x2_ ty = (f32x2_){S[0], S[1]} * (f32x2_){rp[0], rp[1]}; ty = (f32x2_){S[2], S[3]} * (f32x2_){rp[2], rp[3]} + ty;
;                 const f32x4 T = S * d4 + vv * k4;
;                 float sa = ta[0] + ta[1];
;                 float yp = ty[0] + ty[1];
;                 sa = dpp_add<0xB1>(sa); yp = dpp_add<0xB1>(yp);
;                 sa = dpp_add<0x4E>(sa); yp = dpp_add<0x4E>(yp);
;                 sa = dpp_add<0x124>(sa); yp = dpp_add<0x124>(yp);
;                 sa = dpp_add<0x128>(sa); yp = dpp_add<0x128>(yp);
;                 if (tk > 0) yk[(tk - 1) >> 4] = (cg_ == ((tk - 1) & 15)) ? yp : yk[(tk - 1) >> 4];
;                 S = sa * b4 + T;
;                 rp = r4;
;                 r4 = nr4; d4 = nd4; k4 = nk4; a4 = na4; b4 = nb4; vv = nvv;
	v_add_f32_dpp v25, v206, v206 quad_perm:[1,0,3,2] row_mask:0xf bank_mask:0xf bound_ctrl:1
	v_pk_mul_f32 v[164:165], v[166:167], v[198:199]
	v_add_f32_dpp v24, v24, v24 quad_perm:[1,0,3,2] row_mask:0xf bank_mask:0xf bound_ctrl:1
	v_add_f32_dpp v25, v25, v25 quad_perm:[2,3,0,1] row_mask:0xf bank_mask:0xf bound_ctrl:1
	v_pk_fma_f32 v[164:165], v[170:171], v[202:203], v[164:165] op_sel_hi:[1,0,1]
	v_add_f32_dpp v24, v24, v24 quad_perm:[2,3,0,1] row_mask:0xf bank_mask:0xf bound_ctrl:1
	v_add_f32_dpp v25, v25, v25 row_ror:4 row_mask:0xf bank_mask:0xf bound_ctrl:1
	v_pk_fma_f32 v[26:27], v[168:169], v[202:203], v[26:27] op_sel_hi:[1,0,1]
	v_add_f32_dpp v166, v24, v24 row_ror:4 row_mask:0xf bank_mask:0xf bound_ctrl:1
	v_add_f32_dpp v24, v25, v25 row_ror:8 row_mask:0xf bank_mask:0xf bound_ctrl:1
	v_pk_fma_f32 v[196:197], v[176:177], v[24:25], v[26:27] op_sel_hi:[1,0,1]
	v_add_f32_dpp v210, v166, v166 row_ror:8 row_mask:0xf bank_mask:0x2 bound_ctrl:1
	v_pk_fma_f32 v[198:199], v[178:179], v[24:25], v[164:165] op_sel_hi:[1,0,1]
	ds_read_b128 v[24:27], v28 offset:39936
	ds_read_b128 v[164:167], v28 offset:40192
	ds_read_b128 v[168:171], v28 offset:40448
	ds_read_b128 v[172:175], v28 offset:40960
	ds_read_b128 v[176:179], v28 offset:41216
	ds_read_b32 v202, v29 offset:40704
	s_waitcnt lgkmcnt(8)
	v_pk_mul_f32 v[190:191], v[190:191], v[198:199]
	v_pk_mul_f32 v[34:35], v[34:35], v[198:199]
	v_pk_fma_f32 v[188:189], v[188:189], v[196:197], v[190:191]
	v_pk_fma_f32 v[32:33], v[32:33], v[196:197], v[34:35]
	v_add_f32_e32 v206, v188, v189
	v_pk_mul_f32 v[34:35], v[180:181], v[196:197]
	v_add_f32_e32 v32, v32, v33
	s_waitcnt lgkmcnt(6)
	v_add_f32_dpp v33, v206, v206 quad_perm:[1,0,3,2] row_mask:0xf bank_mask:0xf bound_ctrl:1
	v_pk_mul_f32 v[180:181], v[182:183], v[198:199]
	v_add_f32_dpp v32, v32, v32 quad_perm:[1,0,3,2] row_mask:0xf bank_mask:0xf bound_ctrl:1
	v_add_f32_dpp v33, v33, v33 quad_perm:[2,3,0,1] row_mask:0xf bank_mask:0xf bound_ctrl:1
	v_pk_fma_f32 v[180:181], v[186:187], v[200:201], v[180:181] op_sel_hi:[1,0,1]
	v_add_f32_dpp v32, v32, v32 quad_perm:[2,3,0,1] row_mask:0xf bank_mask:0xf bound_ctrl:1
	v_add_f32_dpp v33, v33, v33 row_ror:4 row_mask:0xf bank_mask:0xf bound_ctrl:1
	v_pk_fma_f32 v[34:35], v[184:185], v[200:201], v[34:35] op_sel_hi:[1,0,1]
	v_add_f32_dpp v182, v32, v32 row_ror:4 row_mask:0xf bank_mask:0xf bound_ctrl:1
	v_add_f32_dpp v32, v33, v33 row_ror:8 row_mask:0xf bank_mask:0xf bound_ctrl:1
	v_pk_fma_f32 v[196:197], v[192:193], v[32:33], v[34:35] op_sel_hi:[1,0,1]
	v_add_f32_dpp v207, v182, v182 row_ror:8 row_mask:0xf bank_mask:0x4 bound_ctrl:1
	v_pk_fma_f32 v[198:199], v[194:195], v[32:33], v[180:181] op_sel_hi:[1,0,1]
	ds_read_b128 v[32:35], v28 offset:41472
	ds_read_b128 v[180:183], v28 offset:41728
	ds_read_b128 v[184:187], v28 offset:41984
	ds_read_b128 v[188:191], v28 offset:42496
	ds_read_b128 v[192:195], v28 offset:42752
	ds_read_b32 v200, v29 offset:42240
	s_waitcnt lgkmcnt(8)
	v_pk_mul_f32 v[174:175], v[174:175], v[198:199]
	v_pk_mul_f32 v[162:163], v[162:163], v[198:199]
	v_pk_fma_f32 v[172:173], v[172:173], v[196:197], v[174:175]
	v_pk_fma_f32 v[160:161], v[160:161], v[196:197], v[162:163]
	v_add_f32_e32 v206, v172, v173
	v_pk_mul_f32 v[162:163], v[164:165], v[196:197]
	v_add_f32_e32 v160, v160, v161
	s_waitcnt lgkmcnt(6)
	v_add_f32_dpp v161, v206, v206 quad_perm:[1,0,3,2] row_mask:0xf bank_mask:0xf bound_ctrl:1
	v_pk_mul_f32 v[164:165], v[166:167], v[198:199]
	v_add_f32_dpp v160, v160, v160 quad_perm:[1,0,3,2] row_mask:0xf bank_mask:0xf bound_ctrl:1
	v_add_f32_dpp v161, v161, v161 quad_perm:[2,3,0,1] row_mask:0xf bank_mask:0xf bound_ctrl:1
	v_pk_fma_f32 v[164:165], v[170:171], v[202:203], v[164:165] op_sel_hi:[1,0,1]
	v_add_f32_dpp v160, v160, v160 quad_perm:[2,3,0,1] row_mask:0xf bank_mask:0xf bound_ctrl:1
	v_add_f32_dpp v161, v161, v161 row_ror:4 row_mask:0xf bank_mask:0xf bound_ctrl:1
	v_pk_fma_f32 v[162:163], v[168:169], v[202:203], v[162:163] op_sel_hi:[1,0,1]
	v_add_f32_dpp v166, v160, v160 row_ror:4 row_mask:0xf bank_mask:0xf bound_ctrl:1
	v_add_f32_dpp v160, v161, v161 row_ror:8 row_mask:0xf bank_mask:0xf bound_ctrl:1
	v_pk_fma_f32 v[196:197], v[176:177], v[160:161], v[162:163] op_sel_hi:[1,0,1]
	v_add_f32_dpp v208, v166, v166 row_ror:8 row_mask:0xf bank_mask:0x4 bound_ctrl:1
	v_pk_fma_f32 v[198:199], v[178:179], v[160:161], v[164:165] op_sel_hi:[1,0,1]
	ds_read_b128 v[160:163], v28 offset:43008
	ds_read_b128 v[164:167], v28 offset:43264
	ds_read_b128 v[168:171], v28 offset:43520
	ds_read_b128 v[172:175], v28 offset:44032
	ds_read_b128 v[176:179], v28 offset:44288
	ds_read_b32 v202, v29 offset:43776
	s_waitcnt lgkmcnt(8)
	v_pk_mul_f32 v[190:191], v[190:191], v[198:199]
	v_pk_mul_f32 v[26:27], v[26:27], v[198:199]
	v_pk_fma_f32 v[188:189], v[188:189], v[196:197], v[190:191]
	v_pk_fma_f32 v[24:25], v[24:25], v[196:197], v[26:27]
	v_add_f32_e32 v206, v188, v189
	v_pk_mul_f32 v[26:27], v[180:181], v[196:197]
	v_add_f32_e32 v24, v24, v25
	s_waitcnt lgkmcnt(6)
	v_add_f32_dpp v25, v206, v206 quad_perm:[1,0,3,2] row_mask:0xf bank_mask:0xf bound_ctrl:1
	v_pk_mul_f32 v[180:181], v[182:183], v[198:199]
	v_add_f32_dpp v24, v24, v24 quad_perm:[1,0,3,2] row_mask:0xf bank_mask:0xf bound_ctrl:1
	v_add_f32_dpp v25, v25, v25 quad_perm:[2,3,0,1] row_mask:0xf bank_mask:0xf bound_ctrl:1
	v_pk_fma_f32 v[180:181], v[186:187], v[200:201], v[180:181] op_sel_hi:[1,0,1]
	v_add_f32_dpp v24, v24, v24 quad_perm:[2,3,0,1] row_mask:0xf bank_mask:0xf bound_ctrl:1
	v_add_f32_dpp v25, v25, v25 row_ror:4 row_mask:0xf bank_mask:0xf bound_ctrl:1
	v_pk_fma_f32 v[26:27], v[184:185], v[200:201], v[26:27] op_sel_hi:[1,0,1]
	v_add_f32_dpp v182, v24, v24 row_ror:4 row_mask:0xf bank_mask:0xf bound_ctrl:1
	v_add_f32_dpp v24, v25, v25 row_ror:8 row_mask:0xf bank_mask:0xf bound_ctrl:1
	v_pk_fma_f32 v[196:197], v[192:193], v[24:25], v[26:27] op_sel_hi:[1,0,1]
	v_add_f32_dpp v209, v182, v182 row_ror:8 row_mask:0xf bank_mask:0x4 bound_ctrl:1
	v_pk_fma_f32 v[198:199], v[194:195], v[24:25], v[180:181] op_sel_hi:[1,0,1]
	ds_read_b128 v[24:27], v28 offset:44544
	ds_read_b128 v[180:183], v28 offset:44800
	ds_read_b128 v[184:187], v28 offset:45056
	ds_read_b128 v[188:191], v28 offset:45568
	ds_read_b128 v[192:195], v28 offset:45824
	ds_read_b32 v200, v29 offset:45312
	s_waitcnt lgkmcnt(8)
; #define LAS __attribute__((address_space(3)))
; __device__ __forceinline__ void rwkv_scan_prompt(const Params& p, LAS unsigned char* lds, int bh, int rq) {
;     ...
;             for (int tk = 0; tk < TC; ++tk) {
;                 f32x4 nr4 = r4, nd4 = d4, nk4 = k4, na4 = a4, nb4 = b4; float nvv = vv;
;                 if (tk < TC - 1) {
;                     const LAS float* o = ob + (tk + 1) * 6 * 64;
;                     nr4 = *(const LAS f32x4*)(o + cg_ * 4); nd4 = *(const LAS f32x4*)(o + 64 + cg_ * 4); nk4 = *(const LAS f32x4*)(o + 128 + cg_ * 4);
;                     na4 = *(const LAS f32x4*)(o + 256 + cg_ * 4); nb4 = *(const LAS f32x4*)(o + 320 + cg_ * 4);
;                     nvv = o[192 + rq * 16 + rloc];
;                 }
;                 __builtin_amdgcn_sched_barrier(0);
;                 typedef float f32x2_ __attribute__((ext_vector_type(2)));
;                 f32x2_ ta = (f32x2_){S[0], S[1]} * (f32x2_){a4[0], a4[1]}; ta = (f32x2_){S[2], S[3]} * (f32x2_){a4[2], a4[3]} + ta;
;                 f32x2_ ty = (f32x2_){S[0], S[1]} * (f32x2_){rp[0], rp[1]}; ty = (f32x2_){S[2], S[3]} * (f32x2_){rp[2], rp[3]} + ty;
;                 const f32x4 T = S * d4 + vv * k4;
;                 float sa = ta[0] + ta[1];
;                 float yp = ty[0] + ty[1];
;                 sa = dpp_add<0xB1>(sa); yp = dpp_add<0xB1>(yp);
;                 sa = dpp_add<0x4E>(sa); yp = dpp_add<0x4E>(yp);
;                 sa = dpp_add<0x124>(sa); yp = dpp_add<0x124>(yp);
;                 sa = dpp_add<0x128>(sa); yp = dpp_add<0x128>(yp);
;                 if (tk > 0) yk[(tk - 1) >> 4] = (cg_ == ((tk - 1) & 15)) ? yp : yk[(tk - 1) >> 4];
;                 S = sa * b4 + T;
;                 rp = r4;
;                 r4 = nr4; d4 = nd4; k4 = nk4; a4 = na4; b4 = nb4; vv = nvv;
	v_pk_mul_f32 v[174:175], v[174:175], v[198:199]
	v_pk_mul_f32 v[34:35], v[34:35], v[198:199]
	v_pk_fma_f32 v[172:173], v[172:173], v[196:197], v[174:175]
	v_pk_fma_f32 v[32:33], v[32:33], v[196:197], v[34:35]
	v_add_f32_e32 v206, v172, v173
	v_pk_mul_f32 v[34:35], v[164:165], v[196:197]
	v_add_f32_e32 v32, v32, v33
	s_waitcnt lgkmcnt(6)
	v_add_f32_dpp v33, v206, v206 quad_perm:[1,0,3,2] row_mask:0xf bank_mask:0xf bound_ctrl:1
	v_pk_mul_f32 v[164:165], v[166:167], v[198:199]
	v_add_f32_dpp v32, v32, v32 quad_perm:[1,0,3,2] row_mask:0xf bank_mask:0xf bound_ctrl:1
	v_add_f32_dpp v33, v33, v33 quad_perm:[2,3,0,1] row_mask:0xf bank_mask:0xf bound_ctrl:1
	v_pk_fma_f32 v[164:165], v[170:171], v[202:203], v[164:165] op_sel_hi:[1,0,1]
	v_add_f32_dpp v32, v32, v32 quad_perm:[2,3,0,1] row_mask:0xf bank_mask:0xf bound_ctrl:1
	v_add_f32_dpp v33, v33, v33 row_ror:4 row_mask:0xf bank_mask:0xf bound_ctrl:1
	v_pk_fma_f32 v[34:35], v[168:169], v[202:203], v[34:35] op_sel_hi:[1,0,1]
	v_add_f32_dpp v166, v32, v32 row_ror:4 row_mask:0xf bank_mask:0xf bound_ctrl:1
	v_add_f32_dpp v32, v33, v33 row_ror:8 row_mask:0xf bank_mask:0xf bound_ctrl:1
	v_pk_fma_f32 v[196:197], v[176:177], v[32:33], v[34:35] op_sel_hi:[1,0,1]
	v_add_f32_dpp v210, v166, v166 row_ror:8 row_mask:0xf bank_mask:0x4 bound_ctrl:1
	v_pk_fma_f32 v[198:199], v[178:179], v[32:33], v[164:165] op_sel_hi:[1,0,1]
	ds_read_b128 v[32:35], v28 offset:46080
	ds_read_b128 v[164:167], v28 offset:46336
	ds_read_b128 v[168:171], v28 offset:46592
	ds_read_b128 v[172:175], v28 offset:47104
	ds_read_b128 v[176:179], v28 offset:47360
	ds_read_b32 v202, v29 offset:46848
	s_waitcnt lgkmcnt(8)
	v_pk_mul_f32 v[190:191], v[190:191], v[198:199]
	v_pk_mul_f32 v[162:163], v[162:163], v[198:199]
	v_pk_fma_f32 v[188:189], v[188:189], v[196:197], v[190:191]
	v_pk_fma_f32 v[160:161], v[160:161], v[196:197], v[162:163]
	v_add_f32_e32 v206, v188, v189
	v_pk_mul_f32 v[162:163], v[180:181], v[196:197]
	v_add_f32_e32 v160, v160, v161
	s_waitcnt lgkmcnt(6)
	v_add_f32_dpp v161, v206, v206 quad_perm:[1,0,3,2] row_mask:0xf bank_mask:0xf bound_ctrl:1
	v_pk_mul_f32 v[180:181], v[182:183], v[198:199]
	v_add_f32_dpp v160, v160, v160 quad_perm:[1,0,3,2] row_mask:0xf bank_mask:0xf bound_ctrl:1
	v_add_f32_dpp v161, v161, v161 quad_perm:[2,3,0,1] row_mask:0xf bank_mask:0xf bound_ctrl:1
	v_pk_fma_f32 v[180:181], v[186:187], v[200:201], v[180:181] op_sel_hi:[1,0,1]
	v_add_f32_dpp v160, v160, v160 quad_perm:[2,3,0,1] row_mask:0xf bank_mask:0xf bound_ctrl:1
	v_add_f32_dpp v161, v161, v161 row_ror:4 row_mask:0xf bank_mask:0xf bound_ctrl:1
	v_pk_fma_f32 v[162:163], v[184:185], v[200:201], v[162:163] op_sel_hi:[1,0,1]
	v_add_f32_dpp v182, v160, v160 row_ror:4 row_mask:0xf bank_mask:0xf bound_ctrl:1
	v_add_f32_dpp v160, v161, v161 row_ror:8 row_mask:0xf bank_mask:0xf bound_ctrl:1
	v_pk_fma_f32 v[196:197], v[192:193], v[160:161], v[162:163] op_sel_hi:[1,0,1]
	v_add_f32_dpp v207, v182, v182 row_ror:8 row_mask:0xf bank_mask:0x8 bound_ctrl:1
	v_pk_fma_f32 v[198:199], v[194:195], v[160:161], v[180:181] op_sel_hi:[1,0,1]
	ds_read_b128 v[160:163], v28 offset:47616
	ds_read_b128 v[180:183], v28 offset:47872
	ds_read_b128 v[184:187], v28 offset:48128
	ds_read_b128 v[188:191], v28 offset:48640
	ds_read_b128 v[192:195], v28 offset:48896
	ds_read_b32 v28, v29 offset:48384
	s_waitcnt lgkmcnt(8)
; #define LAS __attribute__((address_space(3)))
; __device__ __forceinline__ void rwkv_scan_prompt(const Params& p, LAS unsigned char* lds, int bh, int rq) {
;     ...
;             for (int tk = 0; tk < TC; ++tk) {
;                 f32x4 nr4 = r4, nd4 = d4, nk4 = k4, na4 = a4, nb4 = b4; float nvv = vv;
;                 if (tk < TC - 1) {
;                     const LAS float* o = ob + (tk + 1) * 6 * 64;
;                     nr4 = *(const LAS f32x4*)(o + cg_ * 4); nd4 = *(const LAS f32x4*)(o + 64 + cg_ * 4); nk4 = *(const LAS f32x4*)(o + 128 + cg_ * 4);
;                     na4 = *(const LAS f32x4*)(o + 256 + cg_ * 4); nb4 = *(const LAS f32x4*)(o + 320 + cg_ * 4);
;                     nvv = o[192 + rq * 16 + rloc];
;                 }
;                 __builtin_amdgcn_sched_barrier(0);
;                 typedef float f32x2_ __attribute__((ext_vector_type(2)));
;                 f32x2_ ta = (f32x2_){S[0], S[1]} * (f32x2_){a4[0], a4[1]}; ta = (f32x2_){S[2], S[3]} * (f32x2_){a4[2], a4[3]} + ta;
;                 f32x2_ ty = (f32x2_){S[0], S[1]} * (f32x2_){rp[0], rp[1]}; ty = (f32x2_){S[2], S[3]} * (f32x2_){rp[2], rp[3]} + ty;
;                 const f32x4 T = S * d4 + vv * k4;
;                 float sa = ta[0] + ta[1];
;                 float yp = ty[0] + ty[1];
;                 sa = dpp_add<0xB1>(sa); yp = dpp_add<0xB1>(yp);
;                 sa = dpp_add<0x4E>(sa); yp = dpp_add<0x4E>(yp);
;                 sa = dpp_add<0x124>(sa); yp = dpp_add<0x124>(yp);
;                 sa = dpp_add<0x128>(sa); yp = dpp_add<0x128>(yp);
;                 if (tk > 0) yk[(tk - 1) >> 4] = (cg_ == ((tk - 1) & 15)) ? yp : yk[(tk - 1) >> 4];
;                 S = sa * b4 + T;
;                 rp = r4;
;                 r4 = nr4; d4 = nd4; k4 = nk4; a4 = na4; b4 = nb4; vv = nvv;
;             }
;             {
;                 float yp = S[0] * rp[0] + S[1] * rp[1] + S[2] * rp[2] + S[3] * rp[3];
;                 yp = row_sum16(yp);
;                 yk[(TC - 1) >> 4] = (cg_ == ((TC - 1) & 15)) ? yp : yk[(TC - 1) >> 4];
;             }
; #pragma unroll
;             for (int j = 0; j < TC / 16; ++j) yk[j] += RKB[buf * TC + j * 16 + cg_] * ob[(j * 16 + cg_) * 6 * 64 + 192 + rq * 16 + rloc];
; #pragma unroll
;             for (int j = 0; j < TC / 16; ++j) YRAW[(size_t)(rowbase + c * TC + j * 16 + cg_) * 512 + h * 64 + rq * 16 + rloc] = yk[j];
	v_pk_mul_f32 v[174:175], v[174:175], v[198:199]
	v_pk_mul_f32 v[26:27], v[26:27], v[198:199]
	v_pk_fma_f32 v[172:173], v[172:173], v[196:197], v[174:175]
	v_pk_fma_f32 v[24:25], v[24:25], v[196:197], v[26:27]
	v_add_f32_e32 v29, v172, v173
	v_add_f32_e32 v24, v24, v25
	v_pk_mul_f32 v[26:27], v[164:165], v[196:197]
	v_add_f32_dpp v25, v29, v29 quad_perm:[1,0,3,2] row_mask:0xf bank_mask:0xf bound_ctrl:1
	v_add_f32_dpp v24, v24, v24 quad_perm:[1,0,3,2] row_mask:0xf bank_mask:0xf bound_ctrl:1
	v_pk_mul_f32 v[164:165], v[166:167], v[198:199]
	v_add_f32_dpp v25, v25, v25 quad_perm:[2,3,0,1] row_mask:0xf bank_mask:0xf bound_ctrl:1
	v_add_f32_dpp v24, v24, v24 quad_perm:[2,3,0,1] row_mask:0xf bank_mask:0xf bound_ctrl:1
	s_waitcnt lgkmcnt(6)
	v_pk_fma_f32 v[164:165], v[170:171], v[202:203], v[164:165] op_sel_hi:[1,0,1]
	v_add_f32_dpp v25, v25, v25 row_ror:4 row_mask:0xf bank_mask:0xf bound_ctrl:1
	v_add_f32_dpp v29, v24, v24 row_ror:4 row_mask:0xf bank_mask:0xf bound_ctrl:1
	v_pk_fma_f32 v[26:27], v[168:169], v[202:203], v[26:27] op_sel_hi:[1,0,1]
	v_add_f32_dpp v24, v25, v25 row_ror:8 row_mask:0xf bank_mask:0xf bound_ctrl:1
	v_add_f32_dpp v208, v29, v29 row_ror:8 row_mask:0xf bank_mask:0x8 bound_ctrl:1
	v_pk_fma_f32 v[26:27], v[176:177], v[24:25], v[26:27] op_sel_hi:[1,0,1]
	v_pk_fma_f32 v[24:25], v[178:179], v[24:25], v[164:165] op_sel_hi:[1,0,1]
	s_waitcnt lgkmcnt(2)
	v_pk_mul_f32 v[164:165], v[190:191], v[24:25]
	v_pk_mul_f32 v[34:35], v[34:35], v[24:25]
	v_pk_fma_f32 v[164:165], v[188:189], v[26:27], v[164:165]
	v_pk_fma_f32 v[32:33], v[32:33], v[26:27], v[34:35]
	v_pk_mul_f32 v[26:27], v[180:181], v[26:27]
	v_pk_mul_f32 v[24:25], v[182:183], v[24:25]
	s_waitcnt lgkmcnt(0)
	v_pk_fma_f32 v[34:35], v[184:185], v[28:29], v[26:27] op_sel_hi:[1,0,1]
	v_add_f32_e32 v26, v164, v165
	v_add_f32_e32 v27, v32, v33
	v_pk_fma_f32 v[24:25], v[186:187], v[28:29], v[24:25] op_sel_hi:[1,0,1]
	v_add_f32_dpp v26, v26, v26 quad_perm:[1,0,3,2] row_mask:0xf bank_mask:0xf bound_ctrl:1
	v_add_f32_dpp v27, v27, v27 quad_perm:[1,0,3,2] row_mask:0xf bank_mask:0xf bound_ctrl:1
	s_lshl_b32 s79, s94, 2
	v_add_f32_dpp v26, v26, v26 quad_perm:[2,3,0,1] row_mask:0xf bank_mask:0xf bound_ctrl:1
	v_add_f32_dpp v27, v27, v27 quad_perm:[2,3,0,1] row_mask:0xf bank_mask:0xf bound_ctrl:1
	s_add_i32 s79, s79, s78
	v_add_f32_dpp v26, v26, v26 row_ror:4 row_mask:0xf bank_mask:0xf bound_ctrl:1
	v_add_f32_dpp v27, v27, v27 row_ror:4 row_mask:0xf bank_mask:0xf bound_ctrl:1
	v_add3_u32 v32, s79, v135, v84
	v_add_f32_dpp v28, v26, v26 row_ror:8 row_mask:0xf bank_mask:0xf bound_ctrl:1
	v_add_f32_dpp v209, v27, v27 row_ror:8 row_mask:0xf bank_mask:0x8 bound_ctrl:1
	v_pk_fma_f32 v[26:27], v[194:195], v[28:29], v[24:25] op_sel_hi:[1,0,1]
	v_pk_fma_f32 v[24:25], v[192:193], v[28:29], v[34:35] op_sel_hi:[1,0,1]
	ds_read2st64_b32 v[32:33], v32 offset0:3 offset1:99
	v_mul_f32_e32 v28, v161, v25
	v_fmac_f32_e32 v28, v160, v24
	v_fmac_f32_e32 v28, v162, v26
	v_fmac_f32_e32 v28, v163, v27
	s_nop 1
	v_add_f32_dpp v34, v28, v28 quad_perm:[1,0,3,2] row_mask:0xf bank_mask:0xf bound_ctrl:1
	v_lshl_add_u32 v28, s95, 7, v126
	ds_read2_b32 v[28:29], v28 offset1:16
	v_add_f32_dpp v34, v34, v34 quad_perm:[2,3,0,1] row_mask:0xf bank_mask:0xf bound_ctrl:1
	s_waitcnt lgkmcnt(0)
	v_fmac_f32_e32 v30, v28, v32
	v_add_f32_dpp v34, v34, v34 row_ror:4 row_mask:0xf bank_mask:0xf bound_ctrl:1
	v_add_u32_e32 v28, s0, v159
	s_nop 0
	v_add_f32_dpp v210, v34, v34 row_ror:8 row_mask:0xf bank_mask:0x8 bound_ctrl:1
	v_cndmask_b32_e64 v31, v207, v208, s[96:97]
	v_cndmask_b32_e64 v31, v31, v209, s[98:99]
	v_cndmask_b32_e64 v31, v31, v210, s[100:101]
	v_fmac_f32_e32 v31, v29, v33
	v_ashrrev_i32_e32 v29, 31, v28
	v_lshlrev_b64 v[32:33], 11, v[28:29]
	v_add_u32_e32 v28, 16, v28
	v_ashrrev_i32_e32 v29, 31, v28
	v_lshlrev_b64 v[28:29], 11, v[28:29]
	v_lshl_add_u64 v[32:33], v[88:89], 0, v[32:33]
	v_lshl_add_u64 v[28:29], v[88:89], 0, v[28:29]
	global_store_dword v[32:33], v30, off sc0 sc1
	global_store_dword v[28:29], v31, off sc0 sc1
